# GEMM K-loops: snake (Gray-code) MFMA order inside each 16-MFMA block, one operand changes per step
# baseline (speedup 1.0000x reference)
.LBB0_58:
	s_add_u32 s0, s56, 0xfffc0080
	s_addc_u32 s1, s57, -1
	s_add_i32 s22, 0, 0x10000
	s_cmp_eq_u32 s64, 12
	s_cselect_b32 s61, s20, s1
	s_cselect_b32 s60, s21, s0
	s_cselect_b32 s59, s51, s63
	s_cselect_b32 s58, s55, s62
	s_add_i32 s37, 0, 0x14000
	v_add_u32_e32 v156, s22, v142
	v_add_u32_e32 v172, s37, v142
	ds_read_b128 v[144:147], v156
	ds_read_b128 v[148:151], v156 offset:1024
	ds_read_b128 v[152:155], v156 offset:2048
	ds_read_b128 v[156:159], v156 offset:3072
	ds_read_b128 v[160:163], v172
	ds_read_b128 v[164:167], v172 offset:1024
	ds_read_b128 v[168:171], v172 offset:2048
	ds_read_b128 v[172:175], v172 offset:3072
	v_lshl_add_u64 v[228:229], s[56:57], 0, v[138:139]
	s_add_i32 m0, s66, 0xc000
	ds_read_b128 v[178:181], v143
	ds_read_b128 v[182:185], v143 offset:1024
	ds_read_b128 v[186:189], v143 offset:2048
	ds_read_b128 v[208:211], v143 offset:3072
	ds_read_b128 v[212:215], v143 offset:4096
	ds_read_b128 v[216:219], v143 offset:5120
	ds_read_b128 v[220:223], v143 offset:6144
	ds_read_b128 v[224:227], v143 offset:7168
	global_load_lds_dwordx4 v[228:229], off
	v_lshl_add_u64 v[228:229], s[56:57], 0, v[140:141]
	s_add_i32 m0, s66, 0xe000
	s_nop 0
	global_load_lds_dwordx4 v[228:229], off
	s_waitcnt vmcnt(8)
	s_waitcnt lgkmcnt(0)
	s_barrier
	s_setprio 1
	s_waitcnt lgkmcnt(0)
	v_mfma_f32_16x16x32_bf16 v[124:127], v[144:147], v[178:181], v[124:127]
	v_mfma_f32_16x16x32_bf16 v[116:119], v[152:155], v[178:181], v[116:119]
	v_mfma_f32_16x16x32_bf16 v[100:103], v[152:155], v[186:189], v[100:103]
	v_mfma_f32_16x16x32_bf16 v[108:111], v[144:147], v[186:189], v[108:111]
	v_mfma_f32_16x16x32_bf16 v[92:95], v[144:147], v[212:215], v[92:95]
	v_mfma_f32_16x16x32_bf16 v[84:87], v[152:155], v[212:215], v[84:87]
	v_mfma_f32_16x16x32_bf16 v[68:71], v[152:155], v[220:223], v[68:71]
	v_mfma_f32_16x16x32_bf16 v[76:79], v[144:147], v[220:223], v[76:79]
	v_mfma_f32_16x16x32_bf16 v[124:127], v[148:151], v[182:185], v[124:127]
	v_mfma_f32_16x16x32_bf16 v[116:119], v[156:159], v[182:185], v[116:119]
	v_mfma_f32_16x16x32_bf16 v[100:103], v[156:159], v[208:211], v[100:103]
	v_mfma_f32_16x16x32_bf16 v[108:111], v[148:151], v[208:211], v[108:111]
	v_mfma_f32_16x16x32_bf16 v[92:95], v[148:151], v[216:219], v[92:95]
	v_mfma_f32_16x16x32_bf16 v[84:87], v[156:159], v[216:219], v[84:87]
	v_mfma_f32_16x16x32_bf16 v[68:71], v[156:159], v[224:227], v[68:71]
	v_mfma_f32_16x16x32_bf16 v[76:79], v[148:151], v[224:227], v[76:79]
	s_setprio 0
	s_setprio 1
	v_mfma_f32_16x16x32_bf16 v[120:123], v[160:163], v[178:181], v[120:123]
	v_mfma_f32_16x16x32_bf16 v[112:115], v[168:171], v[178:181], v[112:115]
	v_mfma_f32_16x16x32_bf16 v[96:99], v[168:171], v[186:189], v[96:99]
	v_mfma_f32_16x16x32_bf16 v[104:107], v[160:163], v[186:189], v[104:107]
	v_mfma_f32_16x16x32_bf16 v[88:91], v[160:163], v[212:215], v[88:91]
	v_mfma_f32_16x16x32_bf16 v[80:83], v[168:171], v[212:215], v[80:83]
	v_mfma_f32_16x16x32_bf16 v[64:67], v[168:171], v[220:223], v[64:67]
	v_mfma_f32_16x16x32_bf16 v[72:75], v[160:163], v[220:223], v[72:75]
	v_mfma_f32_16x16x32_bf16 v[120:123], v[164:167], v[182:185], v[120:123]
	v_mfma_f32_16x16x32_bf16 v[112:115], v[172:175], v[182:185], v[112:115]
	v_mfma_f32_16x16x32_bf16 v[96:99], v[172:175], v[208:211], v[96:99]
	v_mfma_f32_16x16x32_bf16 v[104:107], v[164:167], v[208:211], v[104:107]
	v_mfma_f32_16x16x32_bf16 v[88:91], v[164:167], v[216:219], v[88:91]
	v_mfma_f32_16x16x32_bf16 v[80:83], v[172:175], v[216:219], v[80:83]
	v_mfma_f32_16x16x32_bf16 v[64:67], v[172:175], v[224:227], v[64:67]
	v_mfma_f32_16x16x32_bf16 v[72:75], v[164:167], v[224:227], v[72:75]
	s_setprio 0
	s_barrier
	s_add_i32 s0, s22, s35
	v_lshl_add_u64 v[228:229], s[58:59], 0, v[132:133]
	s_mov_b32 m0, s0
	ds_read_b128 v[178:181], v143 offset:16384
	ds_read_b128 v[182:185], v143 offset:17408
	ds_read_b128 v[186:189], v143 offset:18432
	ds_read_b128 v[208:211], v143 offset:19456
	ds_read_b128 v[212:215], v143 offset:20480
	ds_read_b128 v[216:219], v143 offset:21504
	ds_read_b128 v[220:223], v143 offset:22528
	ds_read_b128 v[224:227], v143 offset:23552
	global_load_lds_dwordx4 v[228:229], off
	s_add_i32 m0, s0, 0x2000
	s_add_u32 s0, s58, 0x10000
	v_lshl_add_u64 v[230:231], s[58:59], 0, v[128:129]
	s_addc_u32 s1, s59, 0
	s_add_i32 s22, s37, s35
	global_load_lds_dwordx4 v[230:231], off
	v_lshl_add_u64 v[232:233], s[0:1], 0, v[132:133]
	s_mov_b32 m0, s22
	v_lshl_add_u64 v[234:235], s[60:61], 0, v[130:131]
	global_load_lds_dwordx4 v[232:233], off
	v_lshl_add_u64 v[232:233], s[0:1], 0, v[128:129]
	s_add_i32 m0, s22, 0x2000
	s_nop 0
	global_load_lds_dwordx4 v[232:233], off
	v_lshl_add_u64 v[232:233], s[60:61], 0, v[134:135]
	s_mov_b32 m0, s66
	s_nop 0
	global_load_lds_dwordx4 v[232:233], off
	s_mov_b32 m0, s67
	s_nop 0
	global_load_lds_dwordx4 v[234:235], off
	s_waitcnt vmcnt(8)
	s_waitcnt lgkmcnt(0)
	s_barrier
	s_setprio 1
	s_waitcnt lgkmcnt(0)
	v_mfma_f32_16x16x32_bf16 v[60:63], v[144:147], v[178:181], v[60:63]
	v_mfma_f32_16x16x32_bf16 v[52:55], v[152:155], v[178:181], v[52:55]
	v_mfma_f32_16x16x32_bf16 v[36:39], v[152:155], v[186:189], v[36:39]
	v_mfma_f32_16x16x32_bf16 v[44:47], v[144:147], v[186:189], v[44:47]
	v_mfma_f32_16x16x32_bf16 v[28:31], v[144:147], v[212:215], v[28:31]
	v_mfma_f32_16x16x32_bf16 v[20:23], v[152:155], v[212:215], v[20:23]
	v_mfma_f32_16x16x32_bf16 v[4:7], v[152:155], v[220:223], v[4:7]
	v_mfma_f32_16x16x32_bf16 v[12:15], v[144:147], v[220:223], v[12:15]
	v_mfma_f32_16x16x32_bf16 v[60:63], v[148:151], v[182:185], v[60:63]
	v_mfma_f32_16x16x32_bf16 v[52:55], v[156:159], v[182:185], v[52:55]
	v_mfma_f32_16x16x32_bf16 v[36:39], v[156:159], v[208:211], v[36:39]
	v_mfma_f32_16x16x32_bf16 v[44:47], v[148:151], v[208:211], v[44:47]
	v_mfma_f32_16x16x32_bf16 v[28:31], v[148:151], v[216:219], v[28:31]
	v_mfma_f32_16x16x32_bf16 v[20:23], v[156:159], v[216:219], v[20:23]
	v_mfma_f32_16x16x32_bf16 v[4:7], v[156:159], v[224:227], v[4:7]
	v_mfma_f32_16x16x32_bf16 v[12:15], v[148:151], v[224:227], v[12:15]
	s_setprio 0
	s_setprio 1
	v_mfma_f32_16x16x32_bf16 v[56:59], v[160:163], v[178:181], v[56:59]
	v_mfma_f32_16x16x32_bf16 v[48:51], v[168:171], v[178:181], v[48:51]
	v_mfma_f32_16x16x32_bf16 v[32:35], v[168:171], v[186:189], v[32:35]
	v_mfma_f32_16x16x32_bf16 v[40:43], v[160:163], v[186:189], v[40:43]
	v_mfma_f32_16x16x32_bf16 v[24:27], v[160:163], v[212:215], v[24:27]
	v_mfma_f32_16x16x32_bf16 v[16:19], v[168:171], v[212:215], v[16:19]
	v_mfma_f32_16x16x32_bf16 v[0:3], v[168:171], v[220:223], v[0:3]
	v_mfma_f32_16x16x32_bf16 v[8:11], v[160:163], v[220:223], v[8:11]
	v_mfma_f32_16x16x32_bf16 v[56:59], v[164:167], v[182:185], v[56:59]
	v_mfma_f32_16x16x32_bf16 v[48:51], v[172:175], v[182:185], v[48:51]
	v_mfma_f32_16x16x32_bf16 v[32:35], v[172:175], v[208:211], v[32:35]
	v_mfma_f32_16x16x32_bf16 v[40:43], v[164:167], v[208:211], v[40:43]
	v_mfma_f32_16x16x32_bf16 v[24:27], v[164:167], v[216:219], v[24:27]
	v_mfma_f32_16x16x32_bf16 v[16:19], v[172:175], v[216:219], v[16:19]
	v_mfma_f32_16x16x32_bf16 v[0:3], v[172:175], v[224:227], v[0:3]
	v_mfma_f32_16x16x32_bf16 v[8:11], v[164:167], v[224:227], v[8:11]
	s_setprio 0
	s_barrier
	s_add_i32 s22, 0, 0x18000
	s_add_i32 s37, 0, 0x1c000
	v_add_u32_e32 v156, s22, v142
	v_add_u32_e32 v172, s37, v142
	ds_read_b128 v[144:147], v156
	ds_read_b128 v[148:151], v156 offset:1024
	ds_read_b128 v[152:155], v156 offset:2048
	ds_read_b128 v[156:159], v156 offset:3072
	ds_read_b128 v[160:163], v172
	ds_read_b128 v[164:167], v172 offset:1024
	ds_read_b128 v[168:171], v172 offset:2048
	ds_read_b128 v[172:175], v172 offset:3072
	s_add_u32 s0, s60, 0x40000
	s_addc_u32 s1, s61, 0
	s_mov_b32 m0, s68
	v_lshl_add_u64 v[236:237], s[0:1], 0, v[134:135]
	ds_read_b128 v[178:181], v143 offset:32768
	ds_read_b128 v[182:185], v143 offset:33792
	ds_read_b128 v[186:189], v143 offset:34816
	ds_read_b128 v[208:211], v143 offset:35840
	ds_read_b128 v[212:215], v143 offset:36864
	ds_read_b128 v[216:219], v143 offset:37888
	ds_read_b128 v[220:223], v143 offset:38912
	ds_read_b128 v[224:227], v143 offset:39936
	global_load_lds_dwordx4 v[236:237], off
	v_lshl_add_u64 v[236:237], s[0:1], 0, v[130:131]
	s_mov_b32 m0, s69
	s_nop 0
	global_load_lds_dwordx4 v[236:237], off
	s_waitcnt vmcnt(8)
	s_waitcnt lgkmcnt(0)
	s_barrier
	s_setprio 1
	s_waitcnt lgkmcnt(0)
	v_mfma_f32_16x16x32_bf16 v[124:127], v[144:147], v[178:181], v[124:127]
	v_mfma_f32_16x16x32_bf16 v[116:119], v[152:155], v[178:181], v[116:119]
	v_mfma_f32_16x16x32_bf16 v[100:103], v[152:155], v[186:189], v[100:103]
	v_mfma_f32_16x16x32_bf16 v[108:111], v[144:147], v[186:189], v[108:111]
	v_mfma_f32_16x16x32_bf16 v[92:95], v[144:147], v[212:215], v[92:95]
	v_mfma_f32_16x16x32_bf16 v[84:87], v[152:155], v[212:215], v[84:87]
	v_mfma_f32_16x16x32_bf16 v[68:71], v[152:155], v[220:223], v[68:71]
	v_mfma_f32_16x16x32_bf16 v[76:79], v[144:147], v[220:223], v[76:79]
	v_mfma_f32_16x16x32_bf16 v[124:127], v[148:151], v[182:185], v[124:127]
	v_mfma_f32_16x16x32_bf16 v[116:119], v[156:159], v[182:185], v[116:119]
	v_mfma_f32_16x16x32_bf16 v[100:103], v[156:159], v[208:211], v[100:103]
	v_mfma_f32_16x16x32_bf16 v[108:111], v[148:151], v[208:211], v[108:111]
	v_mfma_f32_16x16x32_bf16 v[92:95], v[148:151], v[216:219], v[92:95]
	v_mfma_f32_16x16x32_bf16 v[84:87], v[156:159], v[216:219], v[84:87]
	v_mfma_f32_16x16x32_bf16 v[68:71], v[156:159], v[224:227], v[68:71]
	v_mfma_f32_16x16x32_bf16 v[76:79], v[148:151], v[224:227], v[76:79]
	s_setprio 0
	s_setprio 1
	v_mfma_f32_16x16x32_bf16 v[120:123], v[160:163], v[178:181], v[120:123]
	v_mfma_f32_16x16x32_bf16 v[112:115], v[168:171], v[178:181], v[112:115]
	v_mfma_f32_16x16x32_bf16 v[96:99], v[168:171], v[186:189], v[96:99]
	v_mfma_f32_16x16x32_bf16 v[104:107], v[160:163], v[186:189], v[104:107]
	v_mfma_f32_16x16x32_bf16 v[88:91], v[160:163], v[212:215], v[88:91]
	v_mfma_f32_16x16x32_bf16 v[80:83], v[168:171], v[212:215], v[80:83]
	v_mfma_f32_16x16x32_bf16 v[64:67], v[168:171], v[220:223], v[64:67]
	v_mfma_f32_16x16x32_bf16 v[72:75], v[160:163], v[220:223], v[72:75]
	v_mfma_f32_16x16x32_bf16 v[120:123], v[164:167], v[182:185], v[120:123]
	v_mfma_f32_16x16x32_bf16 v[112:115], v[172:175], v[182:185], v[112:115]
	v_mfma_f32_16x16x32_bf16 v[96:99], v[172:175], v[208:211], v[96:99]
	v_mfma_f32_16x16x32_bf16 v[104:107], v[164:167], v[208:211], v[104:107]
	v_mfma_f32_16x16x32_bf16 v[88:91], v[164:167], v[216:219], v[88:91]
	v_mfma_f32_16x16x32_bf16 v[80:83], v[172:175], v[216:219], v[80:83]
	v_mfma_f32_16x16x32_bf16 v[64:67], v[172:175], v[224:227], v[64:67]
	v_mfma_f32_16x16x32_bf16 v[72:75], v[164:167], v[224:227], v[72:75]
	s_setprio 0
	s_barrier
	s_add_i32 s0, s22, s35
	v_lshl_add_u64 v[228:229], v[228:229], 0, s[26:27]
	s_mov_b32 m0, s0
	ds_read_b128 v[178:181], v143 offset:49152
	ds_read_b128 v[182:185], v143 offset:50176
	ds_read_b128 v[186:189], v143 offset:51200
	ds_read_b128 v[208:211], v143 offset:52224
	ds_read_b128 v[212:215], v143 offset:53248
	ds_read_b128 v[216:219], v143 offset:54272
	ds_read_b128 v[220:223], v143 offset:55296
	ds_read_b128 v[224:227], v143 offset:56320
	global_load_lds_dwordx4 v[228:229], off
	s_add_i32 m0, s0, 0x2000
	s_add_u32 s0, s58, 0x10080
	v_lshl_add_u64 v[228:229], v[230:231], 0, s[26:27]
	s_addc_u32 s1, s59, 0
	s_add_i32 s22, s37, s35
	global_load_lds_dwordx4 v[228:229], off
	v_lshl_add_u64 v[228:229], s[0:1], 0, v[132:133]
	s_mov_b32 m0, s22
	s_nop 0
	global_load_lds_dwordx4 v[228:229], off
	v_lshl_add_u64 v[228:229], s[0:1], 0, v[128:129]
	s_add_i32 m0, s22, 0x2000
	s_nop 0
	global_load_lds_dwordx4 v[228:229], off
	v_lshl_add_u64 v[228:229], v[232:233], 0, s[26:27]
	s_mov_b32 m0, s48
	s_nop 0
	global_load_lds_dwordx4 v[228:229], off
	v_lshl_add_u64 v[228:229], v[234:235], 0, s[26:27]
	s_mov_b32 m0, s49
	s_nop 0
	global_load_lds_dwordx4 v[228:229], off
	s_waitcnt vmcnt(8)
	s_waitcnt lgkmcnt(0)
	s_barrier
	s_setprio 1
	s_waitcnt lgkmcnt(0)
	v_mfma_f32_16x16x32_bf16 v[60:63], v[144:147], v[178:181], v[60:63]
	v_mfma_f32_16x16x32_bf16 v[52:55], v[152:155], v[178:181], v[52:55]
	v_mfma_f32_16x16x32_bf16 v[36:39], v[152:155], v[186:189], v[36:39]
	v_mfma_f32_16x16x32_bf16 v[44:47], v[144:147], v[186:189], v[44:47]
	v_mfma_f32_16x16x32_bf16 v[28:31], v[144:147], v[212:215], v[28:31]
	v_mfma_f32_16x16x32_bf16 v[20:23], v[152:155], v[212:215], v[20:23]
	v_mfma_f32_16x16x32_bf16 v[4:7], v[152:155], v[220:223], v[4:7]
	v_mfma_f32_16x16x32_bf16 v[12:15], v[144:147], v[220:223], v[12:15]
	v_mfma_f32_16x16x32_bf16 v[60:63], v[148:151], v[182:185], v[60:63]
	v_mfma_f32_16x16x32_bf16 v[52:55], v[156:159], v[182:185], v[52:55]
	v_mfma_f32_16x16x32_bf16 v[36:39], v[156:159], v[208:211], v[36:39]
	v_mfma_f32_16x16x32_bf16 v[44:47], v[148:151], v[208:211], v[44:47]
	v_mfma_f32_16x16x32_bf16 v[28:31], v[148:151], v[216:219], v[28:31]
	v_mfma_f32_16x16x32_bf16 v[20:23], v[156:159], v[216:219], v[20:23]
	v_mfma_f32_16x16x32_bf16 v[4:7], v[156:159], v[224:227], v[4:7]
	v_mfma_f32_16x16x32_bf16 v[12:15], v[148:151], v[224:227], v[12:15]
	s_setprio 0
	s_setprio 1
	v_mfma_f32_16x16x32_bf16 v[56:59], v[160:163], v[178:181], v[56:59]
	v_mfma_f32_16x16x32_bf16 v[48:51], v[168:171], v[178:181], v[48:51]
	v_mfma_f32_16x16x32_bf16 v[32:35], v[168:171], v[186:189], v[32:35]
	v_mfma_f32_16x16x32_bf16 v[40:43], v[160:163], v[186:189], v[40:43]
	v_mfma_f32_16x16x32_bf16 v[24:27], v[160:163], v[212:215], v[24:27]
	v_mfma_f32_16x16x32_bf16 v[16:19], v[168:171], v[212:215], v[16:19]
	v_mfma_f32_16x16x32_bf16 v[0:3], v[168:171], v[220:223], v[0:3]
	v_mfma_f32_16x16x32_bf16 v[8:11], v[160:163], v[220:223], v[8:11]
	v_mfma_f32_16x16x32_bf16 v[56:59], v[164:167], v[182:185], v[56:59]
	v_mfma_f32_16x16x32_bf16 v[48:51], v[172:175], v[182:185], v[48:51]
	v_mfma_f32_16x16x32_bf16 v[32:35], v[172:175], v[208:211], v[32:35]
	v_mfma_f32_16x16x32_bf16 v[40:43], v[164:167], v[208:211], v[40:43]
	v_mfma_f32_16x16x32_bf16 v[24:27], v[164:167], v[216:219], v[24:27]
	v_mfma_f32_16x16x32_bf16 v[16:19], v[172:175], v[216:219], v[16:19]
	v_mfma_f32_16x16x32_bf16 v[0:3], v[172:175], v[224:227], v[0:3]
	v_mfma_f32_16x16x32_bf16 v[8:11], v[164:167], v[224:227], v[8:11]
	s_setprio 0
	s_barrier
	s_add_i32 s64, s64, 2
	s_add_u32 s56, s56, 0x100
	s_addc_u32 s57, s57, 0
	s_add_u32 s62, s62, 0x100
	s_addc_u32 s63, s63, 0
	s_cmp_gt_u32 s64, 13
	s_cbranch_scc0 .LBB0_58
	v_readlane_b32 s0, v252, 28
	v_readlane_b32 s1, v252, 29
	s_and_b64 vcc, exec, s[0:1]
	s_cbranch_vccz .LBB0_61
	s_barrier

.LBB0_116:
	s_add_u32 s0, s56, 0xfffc0080
	s_addc_u32 s37, s57, -1
	s_add_i32 s39, 0, 0x10000
	s_cmp_eq_u32 s70, 12
	s_cselect_b32 s61, s20, s37
	s_cselect_b32 s60, s21, s0
	s_cselect_b32 s59, s62, s65
	s_cselect_b32 s58, s63, s64
	s_add_i32 s0, 0, 0x14000
	v_add_u32_e32 v168, s39, v180
	v_add_u32_e32 v178, s0, v180
	ds_read_b128 v[128:131], v168
	ds_read_b128 v[132:135], v168 offset:1024
	ds_read_b128 v[164:167], v168 offset:2048
	ds_read_b128 v[168:171], v168 offset:3072
	ds_read_b128 v[172:175], v178
	ds_read_b128 v[182:185], v178 offset:1024
	ds_read_b128 v[186:189], v178 offset:2048
	ds_read_b128 v[208:211], v178 offset:3072
	v_lshl_add_u64 v[178:179], s[56:57], 0, v[160:161]
	s_add_i32 m0, s66, 0xc000
	ds_read_b128 v[212:215], v181
	ds_read_b128 v[216:219], v181 offset:1024
	ds_read_b128 v[220:223], v181 offset:2048
	ds_read_b128 v[224:227], v181 offset:3072
	ds_read_b128 v[228:231], v181 offset:4096
	ds_read_b128 v[232:235], v181 offset:5120
	ds_read_b128 v[236:239], v181 offset:6144
	ds_read_b128 v[240:243], v181 offset:7168
	global_load_lds_dwordx4 v[178:179], off
	v_lshl_add_u64 v[178:179], s[56:57], 0, v[162:163]
	s_add_i32 m0, s66, 0xe000
	s_nop 0
	global_load_lds_dwordx4 v[178:179], off
	s_waitcnt vmcnt(8)
	s_waitcnt lgkmcnt(0)
	s_barrier
	s_setprio 1
	s_waitcnt lgkmcnt(0)
	v_mfma_f32_16x16x32_bf16 v[124:127], v[128:131], v[212:215], v[124:127]
	v_mfma_f32_16x16x32_bf16 v[120:123], v[164:167], v[212:215], v[120:123]
	v_mfma_f32_16x16x32_bf16 v[112:115], v[164:167], v[220:223], v[112:115]
	v_mfma_f32_16x16x32_bf16 v[116:119], v[128:131], v[220:223], v[116:119]
	v_mfma_f32_16x16x32_bf16 v[108:111], v[128:131], v[228:231], v[108:111]
	v_mfma_f32_16x16x32_bf16 v[104:107], v[164:167], v[228:231], v[104:107]
	v_mfma_f32_16x16x32_bf16 v[96:99], v[164:167], v[236:239], v[96:99]
	v_mfma_f32_16x16x32_bf16 v[100:103], v[128:131], v[236:239], v[100:103]
	v_mfma_f32_16x16x32_bf16 v[124:127], v[132:135], v[216:219], v[124:127]
	v_mfma_f32_16x16x32_bf16 v[120:123], v[168:171], v[216:219], v[120:123]
	v_mfma_f32_16x16x32_bf16 v[112:115], v[168:171], v[224:227], v[112:115]
	v_mfma_f32_16x16x32_bf16 v[116:119], v[132:135], v[224:227], v[116:119]
	v_mfma_f32_16x16x32_bf16 v[108:111], v[132:135], v[232:235], v[108:111]
	v_mfma_f32_16x16x32_bf16 v[104:107], v[168:171], v[232:235], v[104:107]
	v_mfma_f32_16x16x32_bf16 v[96:99], v[168:171], v[240:243], v[96:99]
	v_mfma_f32_16x16x32_bf16 v[100:103], v[132:135], v[240:243], v[100:103]
	s_setprio 0
	s_setprio 1
	v_mfma_f32_16x16x32_bf16 v[60:63], v[172:175], v[212:215], v[60:63]
	v_mfma_f32_16x16x32_bf16 v[56:59], v[186:189], v[212:215], v[56:59]
	v_mfma_f32_16x16x32_bf16 v[48:51], v[186:189], v[220:223], v[48:51]
	v_mfma_f32_16x16x32_bf16 v[52:55], v[172:175], v[220:223], v[52:55]
	v_mfma_f32_16x16x32_bf16 v[44:47], v[172:175], v[228:231], v[44:47]
	v_mfma_f32_16x16x32_bf16 v[40:43], v[186:189], v[228:231], v[40:43]
	v_mfma_f32_16x16x32_bf16 v[32:35], v[186:189], v[236:239], v[32:35]
	v_mfma_f32_16x16x32_bf16 v[36:39], v[172:175], v[236:239], v[36:39]
	v_mfma_f32_16x16x32_bf16 v[60:63], v[182:185], v[216:219], v[60:63]
	v_mfma_f32_16x16x32_bf16 v[56:59], v[208:211], v[216:219], v[56:59]
	v_mfma_f32_16x16x32_bf16 v[48:51], v[208:211], v[224:227], v[48:51]
	v_mfma_f32_16x16x32_bf16 v[52:55], v[182:185], v[224:227], v[52:55]
	v_mfma_f32_16x16x32_bf16 v[44:47], v[182:185], v[232:235], v[44:47]
	v_mfma_f32_16x16x32_bf16 v[40:43], v[208:211], v[232:235], v[40:43]
	v_mfma_f32_16x16x32_bf16 v[32:35], v[208:211], v[240:243], v[32:35]
	v_mfma_f32_16x16x32_bf16 v[36:39], v[182:185], v[240:243], v[36:39]
	s_setprio 0
	s_barrier
	s_add_i32 s37, s39, s35
	v_lshl_add_u64 v[178:179], s[58:59], 0, v[140:141]
	s_mov_b32 m0, s37
	ds_read_b128 v[212:215], v181 offset:16384
	ds_read_b128 v[216:219], v181 offset:17408
	ds_read_b128 v[220:223], v181 offset:18432
	ds_read_b128 v[224:227], v181 offset:19456
	ds_read_b128 v[228:231], v181 offset:20480
	ds_read_b128 v[232:235], v181 offset:21504
	ds_read_b128 v[236:239], v181 offset:22528
	ds_read_b128 v[240:243], v181 offset:23552
	global_load_lds_dwordx4 v[178:179], off
	s_add_i32 m0, s37, 0x2000
	s_add_u32 s52, s58, 0x10000
	v_lshl_add_u64 v[244:245], s[58:59], 0, v[136:137]
	s_addc_u32 s53, s59, 0
	s_add_i32 s0, s0, s35
	global_load_lds_dwordx4 v[244:245], off
	v_lshl_add_u64 v[246:247], s[52:53], 0, v[140:141]
	s_mov_b32 m0, s0
	v_lshl_add_u64 v[248:249], s[60:61], 0, v[138:139]
	global_load_lds_dwordx4 v[246:247], off
	v_lshl_add_u64 v[246:247], s[52:53], 0, v[136:137]
	s_add_i32 m0, s0, 0x2000
	s_nop 0
	global_load_lds_dwordx4 v[246:247], off
	v_lshl_add_u64 v[246:247], s[60:61], 0, v[142:143]
	s_mov_b32 m0, s66
	s_nop 0
	global_load_lds_dwordx4 v[246:247], off
	s_mov_b32 m0, s67
	s_nop 0
	global_load_lds_dwordx4 v[248:249], off
	s_waitcnt vmcnt(8)
	s_waitcnt lgkmcnt(0)
	s_barrier
	s_setprio 1
	s_waitcnt lgkmcnt(0)
	v_mfma_f32_16x16x32_bf16 v[92:95], v[128:131], v[212:215], v[92:95]
	v_mfma_f32_16x16x32_bf16 v[88:91], v[164:167], v[212:215], v[88:91]
	v_mfma_f32_16x16x32_bf16 v[80:83], v[164:167], v[220:223], v[80:83]
	v_mfma_f32_16x16x32_bf16 v[84:87], v[128:131], v[220:223], v[84:87]
	v_mfma_f32_16x16x32_bf16 v[76:79], v[128:131], v[228:231], v[76:79]
	v_mfma_f32_16x16x32_bf16 v[72:75], v[164:167], v[228:231], v[72:75]
	v_mfma_f32_16x16x32_bf16 v[64:67], v[164:167], v[236:239], v[64:67]
	v_mfma_f32_16x16x32_bf16 v[68:71], v[128:131], v[236:239], v[68:71]
	v_mfma_f32_16x16x32_bf16 v[92:95], v[132:135], v[216:219], v[92:95]
	v_mfma_f32_16x16x32_bf16 v[88:91], v[168:171], v[216:219], v[88:91]
	v_mfma_f32_16x16x32_bf16 v[80:83], v[168:171], v[224:227], v[80:83]
	v_mfma_f32_16x16x32_bf16 v[84:87], v[132:135], v[224:227], v[84:87]
	v_mfma_f32_16x16x32_bf16 v[76:79], v[132:135], v[232:235], v[76:79]
	v_mfma_f32_16x16x32_bf16 v[72:75], v[168:171], v[232:235], v[72:75]
	v_mfma_f32_16x16x32_bf16 v[64:67], v[168:171], v[240:243], v[64:67]
	v_mfma_f32_16x16x32_bf16 v[68:71], v[132:135], v[240:243], v[68:71]
	s_setprio 0
	s_setprio 1
	v_mfma_f32_16x16x32_bf16 v[28:31], v[172:175], v[212:215], v[28:31]
	v_mfma_f32_16x16x32_bf16 v[24:27], v[186:189], v[212:215], v[24:27]
	v_mfma_f32_16x16x32_bf16 v[16:19], v[186:189], v[220:223], v[16:19]
	v_mfma_f32_16x16x32_bf16 v[20:23], v[172:175], v[220:223], v[20:23]
	v_mfma_f32_16x16x32_bf16 v[12:15], v[172:175], v[228:231], v[12:15]
	v_mfma_f32_16x16x32_bf16 v[8:11], v[186:189], v[228:231], v[8:11]
	v_mfma_f32_16x16x32_bf16 v[0:3], v[186:189], v[236:239], v[0:3]
	v_mfma_f32_16x16x32_bf16 v[4:7], v[172:175], v[236:239], v[4:7]
	v_mfma_f32_16x16x32_bf16 v[28:31], v[182:185], v[216:219], v[28:31]
	v_mfma_f32_16x16x32_bf16 v[24:27], v[208:211], v[216:219], v[24:27]
	v_mfma_f32_16x16x32_bf16 v[16:19], v[208:211], v[224:227], v[16:19]
	v_mfma_f32_16x16x32_bf16 v[20:23], v[182:185], v[224:227], v[20:23]
	v_mfma_f32_16x16x32_bf16 v[12:15], v[182:185], v[232:235], v[12:15]
	v_mfma_f32_16x16x32_bf16 v[8:11], v[208:211], v[232:235], v[8:11]
	v_mfma_f32_16x16x32_bf16 v[0:3], v[208:211], v[240:243], v[0:3]
	v_mfma_f32_16x16x32_bf16 v[4:7], v[182:185], v[240:243], v[4:7]
	s_setprio 0
	s_barrier
	s_add_i32 s0, 0, 0x18000
	s_add_i32 s37, 0, 0x1c000
	v_add_u32_e32 v168, s0, v180
	v_add_u32_e32 v207, s37, v180
	ds_read_b128 v[128:131], v168
	ds_read_b128 v[132:135], v168 offset:1024
	ds_read_b128 v[164:167], v168 offset:2048
	ds_read_b128 v[168:171], v168 offset:3072
	ds_read_b128 v[172:175], v207
	ds_read_b128 v[182:185], v207 offset:1024
	ds_read_b128 v[186:189], v207 offset:2048
	ds_read_b128 v[208:211], v207 offset:3072
	s_add_u32 s52, s60, 0x40000
	s_addc_u32 s53, s61, 0
	s_mov_b32 m0, s68
	v_lshl_add_u64 v[250:251], s[52:53], 0, v[142:143]
	ds_read_b128 v[212:215], v181 offset:32768
	ds_read_b128 v[216:219], v181 offset:33792
	ds_read_b128 v[220:223], v181 offset:34816
	ds_read_b128 v[224:227], v181 offset:35840
	ds_read_b128 v[228:231], v181 offset:36864
	ds_read_b128 v[232:235], v181 offset:37888
	ds_read_b128 v[236:239], v181 offset:38912
	ds_read_b128 v[240:243], v181 offset:39936
	global_load_lds_dwordx4 v[250:251], off
	v_lshl_add_u64 v[250:251], s[52:53], 0, v[138:139]
	s_mov_b32 m0, s69
	s_nop 0
	global_load_lds_dwordx4 v[250:251], off
	s_waitcnt vmcnt(8)
	s_waitcnt lgkmcnt(0)
	s_barrier
	s_setprio 1
	s_waitcnt lgkmcnt(0)
	v_mfma_f32_16x16x32_bf16 v[124:127], v[128:131], v[212:215], v[124:127]
	v_mfma_f32_16x16x32_bf16 v[120:123], v[164:167], v[212:215], v[120:123]
	v_mfma_f32_16x16x32_bf16 v[112:115], v[164:167], v[220:223], v[112:115]
	v_mfma_f32_16x16x32_bf16 v[116:119], v[128:131], v[220:223], v[116:119]
	v_mfma_f32_16x16x32_bf16 v[108:111], v[128:131], v[228:231], v[108:111]
	v_mfma_f32_16x16x32_bf16 v[104:107], v[164:167], v[228:231], v[104:107]
	v_mfma_f32_16x16x32_bf16 v[96:99], v[164:167], v[236:239], v[96:99]
	v_mfma_f32_16x16x32_bf16 v[100:103], v[128:131], v[236:239], v[100:103]
	v_mfma_f32_16x16x32_bf16 v[124:127], v[132:135], v[216:219], v[124:127]
	v_mfma_f32_16x16x32_bf16 v[120:123], v[168:171], v[216:219], v[120:123]
	v_mfma_f32_16x16x32_bf16 v[112:115], v[168:171], v[224:227], v[112:115]
	v_mfma_f32_16x16x32_bf16 v[116:119], v[132:135], v[224:227], v[116:119]
	v_mfma_f32_16x16x32_bf16 v[108:111], v[132:135], v[232:235], v[108:111]
	v_mfma_f32_16x16x32_bf16 v[104:107], v[168:171], v[232:235], v[104:107]
	v_mfma_f32_16x16x32_bf16 v[96:99], v[168:171], v[240:243], v[96:99]
	v_mfma_f32_16x16x32_bf16 v[100:103], v[132:135], v[240:243], v[100:103]
	s_setprio 0
	s_setprio 1
	v_mfma_f32_16x16x32_bf16 v[60:63], v[172:175], v[212:215], v[60:63]
	v_mfma_f32_16x16x32_bf16 v[56:59], v[186:189], v[212:215], v[56:59]
	v_mfma_f32_16x16x32_bf16 v[48:51], v[186:189], v[220:223], v[48:51]
	v_mfma_f32_16x16x32_bf16 v[52:55], v[172:175], v[220:223], v[52:55]
	v_mfma_f32_16x16x32_bf16 v[44:47], v[172:175], v[228:231], v[44:47]
	v_mfma_f32_16x16x32_bf16 v[40:43], v[186:189], v[228:231], v[40:43]
	v_mfma_f32_16x16x32_bf16 v[32:35], v[186:189], v[236:239], v[32:35]
	v_mfma_f32_16x16x32_bf16 v[36:39], v[172:175], v[236:239], v[36:39]
	v_mfma_f32_16x16x32_bf16 v[60:63], v[182:185], v[216:219], v[60:63]
	v_mfma_f32_16x16x32_bf16 v[56:59], v[208:211], v[216:219], v[56:59]
	v_mfma_f32_16x16x32_bf16 v[48:51], v[208:211], v[224:227], v[48:51]
	v_mfma_f32_16x16x32_bf16 v[52:55], v[182:185], v[224:227], v[52:55]
	v_mfma_f32_16x16x32_bf16 v[44:47], v[182:185], v[232:235], v[44:47]
	v_mfma_f32_16x16x32_bf16 v[40:43], v[208:211], v[232:235], v[40:43]
	v_mfma_f32_16x16x32_bf16 v[32:35], v[208:211], v[240:243], v[32:35]
	v_mfma_f32_16x16x32_bf16 v[36:39], v[182:185], v[240:243], v[36:39]
	s_setprio 0
	s_barrier
	s_add_i32 s0, s0, s35
	v_lshl_add_u64 v[178:179], v[178:179], 0, s[26:27]
	s_mov_b32 m0, s0
	ds_read_b128 v[212:215], v181 offset:49152
	ds_read_b128 v[216:219], v181 offset:50176
	ds_read_b128 v[220:223], v181 offset:51200
	ds_read_b128 v[224:227], v181 offset:52224
	ds_read_b128 v[228:231], v181 offset:53248
	ds_read_b128 v[232:235], v181 offset:54272
	ds_read_b128 v[236:239], v181 offset:55296
	ds_read_b128 v[240:243], v181 offset:56320
	global_load_lds_dwordx4 v[178:179], off
	s_add_i32 m0, s0, 0x2000
	s_add_u32 s52, s58, 0x10080
	v_lshl_add_u64 v[178:179], v[244:245], 0, s[26:27]
	s_addc_u32 s53, s59, 0
	s_add_i32 s0, s37, s35
	global_load_lds_dwordx4 v[178:179], off
	v_lshl_add_u64 v[178:179], s[52:53], 0, v[140:141]
	s_mov_b32 m0, s0
	s_nop 0
	global_load_lds_dwordx4 v[178:179], off
	v_lshl_add_u64 v[178:179], s[52:53], 0, v[136:137]
	s_add_i32 m0, s0, 0x2000
	s_nop 0
	global_load_lds_dwordx4 v[178:179], off
	v_lshl_add_u64 v[178:179], v[246:247], 0, s[26:27]
	s_mov_b32 m0, s48
	s_nop 0
	global_load_lds_dwordx4 v[178:179], off
	v_lshl_add_u64 v[178:179], v[248:249], 0, s[26:27]
	s_mov_b32 m0, s49
	s_nop 0
	global_load_lds_dwordx4 v[178:179], off
	s_waitcnt vmcnt(8)
	s_waitcnt lgkmcnt(0)
	s_barrier
	s_setprio 1
	s_waitcnt lgkmcnt(0)
	v_mfma_f32_16x16x32_bf16 v[92:95], v[128:131], v[212:215], v[92:95]
	v_mfma_f32_16x16x32_bf16 v[88:91], v[164:167], v[212:215], v[88:91]
	v_mfma_f32_16x16x32_bf16 v[80:83], v[164:167], v[220:223], v[80:83]
	v_mfma_f32_16x16x32_bf16 v[84:87], v[128:131], v[220:223], v[84:87]
	v_mfma_f32_16x16x32_bf16 v[76:79], v[128:131], v[228:231], v[76:79]
	v_mfma_f32_16x16x32_bf16 v[72:75], v[164:167], v[228:231], v[72:75]
	v_mfma_f32_16x16x32_bf16 v[64:67], v[164:167], v[236:239], v[64:67]
	v_mfma_f32_16x16x32_bf16 v[68:71], v[128:131], v[236:239], v[68:71]
	v_mfma_f32_16x16x32_bf16 v[92:95], v[132:135], v[216:219], v[92:95]
	v_mfma_f32_16x16x32_bf16 v[88:91], v[168:171], v[216:219], v[88:91]
	v_mfma_f32_16x16x32_bf16 v[80:83], v[168:171], v[224:227], v[80:83]
	v_mfma_f32_16x16x32_bf16 v[84:87], v[132:135], v[224:227], v[84:87]
	v_mfma_f32_16x16x32_bf16 v[76:79], v[132:135], v[232:235], v[76:79]
	v_mfma_f32_16x16x32_bf16 v[72:75], v[168:171], v[232:235], v[72:75]
	v_mfma_f32_16x16x32_bf16 v[64:67], v[168:171], v[240:243], v[64:67]
	v_mfma_f32_16x16x32_bf16 v[68:71], v[132:135], v[240:243], v[68:71]
	s_setprio 0
	s_setprio 1
	v_mfma_f32_16x16x32_bf16 v[28:31], v[172:175], v[212:215], v[28:31]
	v_mfma_f32_16x16x32_bf16 v[24:27], v[186:189], v[212:215], v[24:27]
	v_mfma_f32_16x16x32_bf16 v[16:19], v[186:189], v[220:223], v[16:19]
	v_mfma_f32_16x16x32_bf16 v[20:23], v[172:175], v[220:223], v[20:23]
	v_mfma_f32_16x16x32_bf16 v[12:15], v[172:175], v[228:231], v[12:15]
	v_mfma_f32_16x16x32_bf16 v[8:11], v[186:189], v[228:231], v[8:11]
	v_mfma_f32_16x16x32_bf16 v[0:3], v[186:189], v[236:239], v[0:3]
	v_mfma_f32_16x16x32_bf16 v[4:7], v[172:175], v[236:239], v[4:7]
	v_mfma_f32_16x16x32_bf16 v[28:31], v[182:185], v[216:219], v[28:31]
	v_mfma_f32_16x16x32_bf16 v[24:27], v[208:211], v[216:219], v[24:27]
	v_mfma_f32_16x16x32_bf16 v[16:19], v[208:211], v[224:227], v[16:19]
	v_mfma_f32_16x16x32_bf16 v[20:23], v[182:185], v[224:227], v[20:23]
	v_mfma_f32_16x16x32_bf16 v[12:15], v[182:185], v[232:235], v[12:15]
	v_mfma_f32_16x16x32_bf16 v[8:11], v[208:211], v[232:235], v[8:11]
	v_mfma_f32_16x16x32_bf16 v[0:3], v[208:211], v[240:243], v[0:3]
	v_mfma_f32_16x16x32_bf16 v[4:7], v[182:185], v[240:243], v[4:7]
	s_setprio 0
	s_barrier
	s_add_i32 s70, s70, 2
	s_add_u32 s56, s56, 0x100
	s_addc_u32 s57, s57, 0
	s_add_u32 s64, s64, 0x100
	s_addc_u32 s65, s65, 0
	s_cmp_gt_u32 s70, 13
	s_cbranch_scc0 .LBB0_116
	v_readlane_b32 s4, v252, 28
	v_readlane_b32 s5, v252, 29
	s_and_b64 vcc, exec, s[4:5]
	s_cbranch_vccz .LBB0_119
	s_barrier

.LBB0_154:
	s_add_u32 s37, s54, 0xfff80080
	s_addc_u32 s39, s55, -1
	s_add_i32 s45, 0, 0x10000
	s_cmp_eq_u32 s30, 4
	s_cselect_b32 s61, s51, s39
	s_cselect_b32 s60, s50, s37
	v_add_u32_e32 v120, s45, v207
	s_cselect_b32 s57, s53, s21
	s_cselect_b32 s56, s52, s20
	s_add_i32 s37, 0, 0x14000
	ds_read_b128 v[130:133], v120
	ds_read_b128 v[134:137], v120 offset:1024
	ds_read_b128 v[138:141], v120 offset:2048
	ds_read_b128 v[142:145], v120 offset:3072
	v_add_u32_e32 v120, s37, v207
	ds_read_b128 v[146:149], v120
	ds_read_b128 v[150:153], v120 offset:1024
	ds_read_b128 v[154:157], v120 offset:2048
	ds_read_b128 v[158:161], v120 offset:3072
	v_lshl_add_u64 v[120:121], s[54:55], 0, v[178:179]
	s_add_i32 m0, s35, 0xc000
	ds_read_b128 v[182:185], v209
	ds_read_b128 v[186:189], v209 offset:1024
	ds_read_b128 v[210:213], v209 offset:2048
	ds_read_b128 v[214:217], v209 offset:3072
	ds_read_b128 v[218:221], v209 offset:4096
	ds_read_b128 v[222:225], v209 offset:5120
	ds_read_b128 v[226:229], v209 offset:6144
	ds_read_b128 v[230:233], v209 offset:7168
	global_load_lds_dwordx4 v[120:121], off
	v_lshl_add_u64 v[120:121], s[54:55], 0, v[180:181]
	s_add_i32 m0, s35, 0xe000
	s_nop 0
	global_load_lds_dwordx4 v[120:121], off
	s_waitcnt vmcnt(8)
	s_waitcnt lgkmcnt(0)
	s_barrier
	s_setprio 1
	s_waitcnt lgkmcnt(0)
	v_mfma_f32_16x16x32_bf16 v[126:129], v[130:133], v[182:185], v[126:129]
	v_mfma_f32_16x16x32_bf16 v[120:123], v[138:141], v[182:185], v[122:125]
	v_mfma_f32_16x16x32_bf16 v[108:111], v[130:133], v[210:213], v[108:111]
	v_mfma_f32_16x16x32_bf16 v[104:107], v[138:141], v[210:213], v[104:107]
	v_mfma_f32_16x16x32_bf16 v[92:95], v[130:133], v[218:221], v[92:95]
	v_mfma_f32_16x16x32_bf16 v[88:91], v[138:141], v[218:221], v[88:91]
	v_mfma_f32_16x16x32_bf16 v[76:79], v[130:133], v[226:229], v[76:79]
	v_mfma_f32_16x16x32_bf16 v[72:75], v[138:141], v[226:229], v[72:75]
	v_mfma_f32_16x16x32_bf16 v[126:129], v[134:137], v[186:189], v[126:129]
	v_mfma_f32_16x16x32_bf16 v[120:123], v[142:145], v[186:189], v[120:123]
	v_mfma_f32_16x16x32_bf16 v[108:111], v[134:137], v[214:217], v[108:111]
	v_mfma_f32_16x16x32_bf16 v[104:107], v[142:145], v[214:217], v[104:107]
	v_mfma_f32_16x16x32_bf16 v[92:95], v[134:137], v[222:225], v[92:95]
	v_mfma_f32_16x16x32_bf16 v[88:91], v[142:145], v[222:225], v[88:91]
	v_mfma_f32_16x16x32_bf16 v[76:79], v[134:137], v[230:233], v[76:79]
	v_mfma_f32_16x16x32_bf16 v[72:75], v[142:145], v[230:233], v[72:75]
	s_setprio 0
	s_setprio 1
	v_mfma_f32_16x16x32_bf16 v[116:119], v[146:149], v[182:185], v[116:119]
	v_mfma_f32_16x16x32_bf16 v[112:115], v[154:157], v[182:185], v[112:115]
	v_mfma_f32_16x16x32_bf16 v[96:99], v[154:157], v[210:213], v[96:99]
	v_mfma_f32_16x16x32_bf16 v[100:103], v[146:149], v[210:213], v[100:103]
	v_mfma_f32_16x16x32_bf16 v[84:87], v[146:149], v[218:221], v[84:87]
	v_mfma_f32_16x16x32_bf16 v[80:83], v[154:157], v[218:221], v[80:83]
	v_mfma_f32_16x16x32_bf16 v[64:67], v[154:157], v[226:229], v[64:67]
	v_mfma_f32_16x16x32_bf16 v[68:71], v[146:149], v[226:229], v[68:71]
	v_mfma_f32_16x16x32_bf16 v[116:119], v[150:153], v[186:189], v[116:119]
	v_mfma_f32_16x16x32_bf16 v[112:115], v[158:161], v[186:189], v[112:115]
	v_mfma_f32_16x16x32_bf16 v[96:99], v[158:161], v[214:217], v[96:99]
	v_mfma_f32_16x16x32_bf16 v[100:103], v[150:153], v[214:217], v[100:103]
	v_mfma_f32_16x16x32_bf16 v[84:87], v[150:153], v[222:225], v[84:87]
	v_mfma_f32_16x16x32_bf16 v[80:83], v[158:161], v[222:225], v[80:83]
	v_mfma_f32_16x16x32_bf16 v[64:67], v[158:161], v[230:233], v[64:67]
	v_mfma_f32_16x16x32_bf16 v[68:71], v[150:153], v[230:233], v[68:71]
	s_setprio 0
	s_barrier
	s_add_i32 s39, s45, s34
	v_lshl_add_u64 v[234:235], s[56:57], 0, v[176:177]
	s_mov_b32 m0, s39
	ds_read_b128 v[182:185], v209 offset:16384
	ds_read_b128 v[186:189], v209 offset:17408
	ds_read_b128 v[210:213], v209 offset:18432
	ds_read_b128 v[214:217], v209 offset:19456
	ds_read_b128 v[218:221], v209 offset:20480
	ds_read_b128 v[222:225], v209 offset:21504
	ds_read_b128 v[226:229], v209 offset:22528
	ds_read_b128 v[230:233], v209 offset:23552
	global_load_lds_dwordx4 v[234:235], off
	s_add_i32 m0, s39, 0x2000
	s_add_u32 s88, s56, 0x20000
	v_lshl_add_u64 v[236:237], s[56:57], 0, v[166:167]
	s_addc_u32 s89, s57, 0
	s_add_i32 s37, s37, s34
	global_load_lds_dwordx4 v[236:237], off
	v_lshl_add_u64 v[124:125], s[88:89], 0, v[176:177]
	s_mov_b32 m0, s37
	v_lshl_add_u64 v[238:239], s[60:61], 0, v[162:163]
	global_load_lds_dwordx4 v[124:125], off
	v_lshl_add_u64 v[124:125], s[88:89], 0, v[166:167]
	s_add_i32 m0, s37, 0x2000
	v_lshl_add_u64 v[240:241], s[60:61], 0, v[164:165]
	global_load_lds_dwordx4 v[124:125], off
	s_mov_b32 m0, s35
	s_nop 0
	global_load_lds_dwordx4 v[238:239], off
	s_mov_b32 m0, s62
	s_nop 0
	global_load_lds_dwordx4 v[240:241], off
	s_waitcnt vmcnt(8)
	s_waitcnt lgkmcnt(0)
	s_barrier
	s_setprio 1
	s_waitcnt lgkmcnt(0)
	v_mfma_f32_16x16x32_bf16 v[60:63], v[130:133], v[182:185], v[60:63]
	v_mfma_f32_16x16x32_bf16 v[56:59], v[138:141], v[182:185], v[56:59]
	v_mfma_f32_16x16x32_bf16 v[40:43], v[138:141], v[210:213], v[40:43]
	v_mfma_f32_16x16x32_bf16 v[44:47], v[130:133], v[210:213], v[44:47]
	v_mfma_f32_16x16x32_bf16 v[28:31], v[130:133], v[218:221], v[28:31]
	v_mfma_f32_16x16x32_bf16 v[24:27], v[138:141], v[218:221], v[24:27]
	v_mfma_f32_16x16x32_bf16 v[8:11], v[138:141], v[226:229], v[8:11]
	v_mfma_f32_16x16x32_bf16 v[12:15], v[130:133], v[226:229], v[12:15]
	v_mfma_f32_16x16x32_bf16 v[60:63], v[134:137], v[186:189], v[60:63]
	v_mfma_f32_16x16x32_bf16 v[56:59], v[142:145], v[186:189], v[56:59]
	v_mfma_f32_16x16x32_bf16 v[40:43], v[142:145], v[214:217], v[40:43]
	v_mfma_f32_16x16x32_bf16 v[44:47], v[134:137], v[214:217], v[44:47]
	v_mfma_f32_16x16x32_bf16 v[28:31], v[134:137], v[222:225], v[28:31]
	v_mfma_f32_16x16x32_bf16 v[24:27], v[142:145], v[222:225], v[24:27]
	v_mfma_f32_16x16x32_bf16 v[8:11], v[142:145], v[230:233], v[8:11]
	v_mfma_f32_16x16x32_bf16 v[12:15], v[134:137], v[230:233], v[12:15]
	s_setprio 0
	s_setprio 1
	v_mfma_f32_16x16x32_bf16 v[52:55], v[146:149], v[182:185], v[52:55]
	v_mfma_f32_16x16x32_bf16 v[48:51], v[154:157], v[182:185], v[48:51]
	v_mfma_f32_16x16x32_bf16 v[32:35], v[154:157], v[210:213], v[32:35]
	v_mfma_f32_16x16x32_bf16 v[36:39], v[146:149], v[210:213], v[36:39]
	v_mfma_f32_16x16x32_bf16 v[20:23], v[146:149], v[218:221], v[20:23]
	v_mfma_f32_16x16x32_bf16 v[16:19], v[154:157], v[218:221], v[16:19]
	v_mfma_f32_16x16x32_bf16 v[0:3], v[154:157], v[226:229], v[0:3]
	v_mfma_f32_16x16x32_bf16 v[4:7], v[146:149], v[226:229], v[4:7]
	v_mfma_f32_16x16x32_bf16 v[52:55], v[150:153], v[186:189], v[52:55]
	v_mfma_f32_16x16x32_bf16 v[48:51], v[158:161], v[186:189], v[48:51]
	v_mfma_f32_16x16x32_bf16 v[32:35], v[158:161], v[214:217], v[32:35]
	v_mfma_f32_16x16x32_bf16 v[36:39], v[150:153], v[214:217], v[36:39]
	v_mfma_f32_16x16x32_bf16 v[20:23], v[150:153], v[222:225], v[20:23]
	v_mfma_f32_16x16x32_bf16 v[16:19], v[158:161], v[222:225], v[16:19]
	v_mfma_f32_16x16x32_bf16 v[0:3], v[158:161], v[230:233], v[0:3]
	v_mfma_f32_16x16x32_bf16 v[4:7], v[150:153], v[230:233], v[4:7]
	s_setprio 0
	s_barrier
	s_add_i32 s37, 0, 0x18000
	v_add_u32_e32 v124, s37, v207
	s_add_i32 s39, 0, 0x1c000
	ds_read_b128 v[130:133], v124
	ds_read_b128 v[134:137], v124 offset:1024
	ds_read_b128 v[138:141], v124 offset:2048
	ds_read_b128 v[142:145], v124 offset:3072
	v_add_u32_e32 v124, s39, v207
	ds_read_b128 v[146:149], v124
	ds_read_b128 v[150:153], v124 offset:1024
	ds_read_b128 v[154:157], v124 offset:2048
	ds_read_b128 v[158:161], v124 offset:3072
	s_add_u32 s60, s60, 0x80000
	s_addc_u32 s61, s61, 0
	s_mov_b32 m0, s63
	v_lshl_add_u64 v[124:125], s[60:61], 0, v[162:163]
	ds_read_b128 v[182:185], v209 offset:32768
	ds_read_b128 v[186:189], v209 offset:33792
	ds_read_b128 v[210:213], v209 offset:34816
	ds_read_b128 v[214:217], v209 offset:35840
	ds_read_b128 v[218:221], v209 offset:36864
	ds_read_b128 v[222:225], v209 offset:37888
	ds_read_b128 v[226:229], v209 offset:38912
	ds_read_b128 v[230:233], v209 offset:39936
	global_load_lds_dwordx4 v[124:125], off
	v_lshl_add_u64 v[124:125], s[60:61], 0, v[164:165]
	s_mov_b32 m0, s64
	s_nop 0
	global_load_lds_dwordx4 v[124:125], off
	s_waitcnt vmcnt(8)
	s_waitcnt lgkmcnt(0)
	s_barrier
	s_setprio 1
	s_waitcnt lgkmcnt(0)
	v_mfma_f32_16x16x32_bf16 v[124:127], v[130:133], v[182:185], v[126:129]
	v_mfma_f32_16x16x32_bf16 v[120:123], v[138:141], v[182:185], v[120:123]
	v_mfma_f32_16x16x32_bf16 v[108:111], v[130:133], v[210:213], v[108:111]
	v_mfma_f32_16x16x32_bf16 v[104:107], v[138:141], v[210:213], v[104:107]
	v_mfma_f32_16x16x32_bf16 v[92:95], v[130:133], v[218:221], v[92:95]
	v_mfma_f32_16x16x32_bf16 v[88:91], v[138:141], v[218:221], v[88:91]
	v_mfma_f32_16x16x32_bf16 v[76:79], v[130:133], v[226:229], v[76:79]
	v_mfma_f32_16x16x32_bf16 v[72:75], v[138:141], v[226:229], v[72:75]
	v_mfma_f32_16x16x32_bf16 v[126:129], v[134:137], v[186:189], v[124:127]
	v_mfma_f32_16x16x32_bf16 v[122:125], v[142:145], v[186:189], v[120:123]
	v_mfma_f32_16x16x32_bf16 v[108:111], v[134:137], v[214:217], v[108:111]
	v_mfma_f32_16x16x32_bf16 v[104:107], v[142:145], v[214:217], v[104:107]
	v_mfma_f32_16x16x32_bf16 v[92:95], v[134:137], v[222:225], v[92:95]
	v_mfma_f32_16x16x32_bf16 v[88:91], v[142:145], v[222:225], v[88:91]
	v_mfma_f32_16x16x32_bf16 v[76:79], v[134:137], v[230:233], v[76:79]
	v_mfma_f32_16x16x32_bf16 v[72:75], v[142:145], v[230:233], v[72:75]
	s_setprio 0
	s_setprio 1
	v_mfma_f32_16x16x32_bf16 v[116:119], v[146:149], v[182:185], v[116:119]
	v_mfma_f32_16x16x32_bf16 v[112:115], v[154:157], v[182:185], v[112:115]
	v_mfma_f32_16x16x32_bf16 v[96:99], v[154:157], v[210:213], v[96:99]
	v_mfma_f32_16x16x32_bf16 v[100:103], v[146:149], v[210:213], v[100:103]
	v_mfma_f32_16x16x32_bf16 v[84:87], v[146:149], v[218:221], v[84:87]
	v_mfma_f32_16x16x32_bf16 v[80:83], v[154:157], v[218:221], v[80:83]
	v_mfma_f32_16x16x32_bf16 v[64:67], v[154:157], v[226:229], v[64:67]
	v_mfma_f32_16x16x32_bf16 v[68:71], v[146:149], v[226:229], v[68:71]
	v_mfma_f32_16x16x32_bf16 v[116:119], v[150:153], v[186:189], v[116:119]
	v_mfma_f32_16x16x32_bf16 v[112:115], v[158:161], v[186:189], v[112:115]
	v_mfma_f32_16x16x32_bf16 v[96:99], v[158:161], v[214:217], v[96:99]
	v_mfma_f32_16x16x32_bf16 v[100:103], v[150:153], v[214:217], v[100:103]
	v_mfma_f32_16x16x32_bf16 v[84:87], v[150:153], v[222:225], v[84:87]
	v_mfma_f32_16x16x32_bf16 v[80:83], v[158:161], v[222:225], v[80:83]
	v_mfma_f32_16x16x32_bf16 v[64:67], v[158:161], v[230:233], v[64:67]
	v_mfma_f32_16x16x32_bf16 v[68:71], v[150:153], v[230:233], v[68:71]
	s_setprio 0
	s_barrier
	s_add_i32 s37, s37, s34
	v_lshl_add_u64 v[120:121], v[234:235], 0, s[26:27]
	s_mov_b32 m0, s37
	ds_read_b128 v[182:185], v209 offset:49152
	ds_read_b128 v[186:189], v209 offset:50176
	ds_read_b128 v[210:213], v209 offset:51200
	ds_read_b128 v[214:217], v209 offset:52224
	ds_read_b128 v[218:221], v209 offset:53248
	ds_read_b128 v[222:225], v209 offset:54272
	ds_read_b128 v[226:229], v209 offset:55296
	ds_read_b128 v[230:233], v209 offset:56320
	global_load_lds_dwordx4 v[120:121], off
	s_add_i32 m0, s37, 0x2000
	s_add_u32 s56, s56, 0x20080
	v_lshl_add_u64 v[120:121], v[236:237], 0, s[26:27]
	s_addc_u32 s57, s57, 0
	s_add_i32 s37, s39, s34
	global_load_lds_dwordx4 v[120:121], off
	v_lshl_add_u64 v[120:121], s[56:57], 0, v[176:177]
	s_mov_b32 m0, s37
	s_nop 0
	global_load_lds_dwordx4 v[120:121], off
	v_lshl_add_u64 v[120:121], s[56:57], 0, v[166:167]
	s_add_i32 m0, s37, 0x2000
	s_nop 0
	global_load_lds_dwordx4 v[120:121], off
	v_lshl_add_u64 v[120:121], v[238:239], 0, s[26:27]
	s_mov_b32 m0, s65
	s_nop 0
	global_load_lds_dwordx4 v[120:121], off
	v_lshl_add_u64 v[120:121], v[240:241], 0, s[26:27]
	s_mov_b32 m0, s66
	s_nop 0
	global_load_lds_dwordx4 v[120:121], off
	s_waitcnt vmcnt(8)
	s_waitcnt lgkmcnt(0)
	s_barrier
	s_setprio 1
	s_waitcnt lgkmcnt(0)
	v_mfma_f32_16x16x32_bf16 v[60:63], v[130:133], v[182:185], v[60:63]
	v_mfma_f32_16x16x32_bf16 v[56:59], v[138:141], v[182:185], v[56:59]
	v_mfma_f32_16x16x32_bf16 v[40:43], v[138:141], v[210:213], v[40:43]
	v_mfma_f32_16x16x32_bf16 v[44:47], v[130:133], v[210:213], v[44:47]
	v_mfma_f32_16x16x32_bf16 v[28:31], v[130:133], v[218:221], v[28:31]
	v_mfma_f32_16x16x32_bf16 v[24:27], v[138:141], v[218:221], v[24:27]
	v_mfma_f32_16x16x32_bf16 v[8:11], v[138:141], v[226:229], v[8:11]
	v_mfma_f32_16x16x32_bf16 v[12:15], v[130:133], v[226:229], v[12:15]
	v_mfma_f32_16x16x32_bf16 v[60:63], v[134:137], v[186:189], v[60:63]
	v_mfma_f32_16x16x32_bf16 v[56:59], v[142:145], v[186:189], v[56:59]
	v_mfma_f32_16x16x32_bf16 v[40:43], v[142:145], v[214:217], v[40:43]
	v_mfma_f32_16x16x32_bf16 v[44:47], v[134:137], v[214:217], v[44:47]
	v_mfma_f32_16x16x32_bf16 v[28:31], v[134:137], v[222:225], v[28:31]
	v_mfma_f32_16x16x32_bf16 v[24:27], v[142:145], v[222:225], v[24:27]
	v_mfma_f32_16x16x32_bf16 v[8:11], v[142:145], v[230:233], v[8:11]
	v_mfma_f32_16x16x32_bf16 v[12:15], v[134:137], v[230:233], v[12:15]
	s_setprio 0
	s_setprio 1
	v_mfma_f32_16x16x32_bf16 v[52:55], v[146:149], v[182:185], v[52:55]
	v_mfma_f32_16x16x32_bf16 v[48:51], v[154:157], v[182:185], v[48:51]
	v_mfma_f32_16x16x32_bf16 v[32:35], v[154:157], v[210:213], v[32:35]
	v_mfma_f32_16x16x32_bf16 v[36:39], v[146:149], v[210:213], v[36:39]
	v_mfma_f32_16x16x32_bf16 v[20:23], v[146:149], v[218:221], v[20:23]
	v_mfma_f32_16x16x32_bf16 v[16:19], v[154:157], v[218:221], v[16:19]
	v_mfma_f32_16x16x32_bf16 v[0:3], v[154:157], v[226:229], v[0:3]
	v_mfma_f32_16x16x32_bf16 v[4:7], v[146:149], v[226:229], v[4:7]
	v_mfma_f32_16x16x32_bf16 v[52:55], v[150:153], v[186:189], v[52:55]
	v_mfma_f32_16x16x32_bf16 v[48:51], v[158:161], v[186:189], v[48:51]
	v_mfma_f32_16x16x32_bf16 v[32:35], v[158:161], v[214:217], v[32:35]
	v_mfma_f32_16x16x32_bf16 v[36:39], v[150:153], v[214:217], v[36:39]
	v_mfma_f32_16x16x32_bf16 v[20:23], v[150:153], v[222:225], v[20:23]
	v_mfma_f32_16x16x32_bf16 v[16:19], v[158:161], v[222:225], v[16:19]
	v_mfma_f32_16x16x32_bf16 v[0:3], v[158:161], v[230:233], v[0:3]
	v_mfma_f32_16x16x32_bf16 v[4:7], v[150:153], v[230:233], v[4:7]
	s_setprio 0
	s_barrier
	s_add_i32 s30, s30, 2
	s_add_u32 s54, s54, 0x100
	s_addc_u32 s55, s55, 0
	s_add_u32 s20, s20, 0x100
	s_addc_u32 s21, s21, 0
	s_cmp_gt_u32 s30, 5
	s_cbranch_scc0 .LBB0_154
	s_and_b64 vcc, exec, s[48:49]
	s_cbranch_vccz .LBB0_157
	s_barrier

.LBB0_645:
	s_add_u32 s37, s42, 0xfffc0080
	s_addc_u32 s39, s43, -1
	s_add_i32 s65, 0, 0x10000
	s_cmp_eq_u32 s64, 12
	s_cselect_b32 s63, s0, s39
	s_cselect_b32 s62, s1, s37
	v_add_u32_e32 v145, s65, v162
	s_cselect_b32 s45, s20, s30
	s_cselect_b32 s44, s21, s22
	s_add_i32 s37, 0, 0x14000
	ds_read_b128 v[146:149], v145
	ds_read_b128 v[150:153], v145 offset:1024
	ds_read_b128 v[154:157], v145 offset:2048
	ds_read_b128 v[170:173], v145 offset:3072
	v_add_u32_e32 v145, s37, v162
	ds_read_b128 v[178:181], v145
	ds_read_b128 v[182:185], v145 offset:1024
	ds_read_b128 v[186:189], v145 offset:2048
	ds_read_b128 v[208:211], v145 offset:3072
	v_lshl_add_u64 v[158:159], s[42:43], 0, v[140:141]
	s_add_i32 m0, s56, 0xc000
	ds_read_b128 v[212:215], v168
	ds_read_b128 v[216:219], v168 offset:1024
	ds_read_b128 v[220:223], v168 offset:2048
	ds_read_b128 v[224:227], v168 offset:3072
	ds_read_b128 v[228:231], v168 offset:4096
	ds_read_b128 v[232:235], v168 offset:5120
	ds_read_b128 v[236:239], v168 offset:6144
	ds_read_b128 v[240:243], v168 offset:7168
	global_load_lds_dwordx4 v[158:159], off
	v_lshl_add_u64 v[158:159], s[42:43], 0, v[142:143]
	s_add_i32 m0, s56, 0xe000
	s_nop 0
	global_load_lds_dwordx4 v[158:159], off
	s_waitcnt vmcnt(8)
	s_waitcnt lgkmcnt(0)
	s_barrier
	s_setprio 1
	s_waitcnt lgkmcnt(0)
	v_mfma_f32_16x16x32_bf16 v[124:127], v[146:149], v[212:215], v[124:127]
	v_mfma_f32_16x16x32_bf16 v[120:123], v[154:157], v[212:215], v[120:123]
	v_mfma_f32_16x16x32_bf16 v[112:115], v[154:157], v[220:223], v[112:115]
	v_mfma_f32_16x16x32_bf16 v[116:119], v[146:149], v[220:223], v[116:119]
	v_mfma_f32_16x16x32_bf16 v[100:103], v[146:149], v[228:231], v[100:103]
	v_mfma_f32_16x16x32_bf16 v[96:99], v[154:157], v[228:231], v[96:99]
	v_mfma_f32_16x16x32_bf16 v[80:83], v[154:157], v[236:239], v[80:83]
	v_mfma_f32_16x16x32_bf16 v[84:87], v[146:149], v[236:239], v[84:87]
	v_mfma_f32_16x16x32_bf16 v[124:127], v[150:153], v[216:219], v[124:127]
	v_mfma_f32_16x16x32_bf16 v[120:123], v[170:173], v[216:219], v[120:123]
	v_mfma_f32_16x16x32_bf16 v[112:115], v[170:173], v[224:227], v[112:115]
	v_mfma_f32_16x16x32_bf16 v[116:119], v[150:153], v[224:227], v[116:119]
	v_mfma_f32_16x16x32_bf16 v[100:103], v[150:153], v[232:235], v[100:103]
	v_mfma_f32_16x16x32_bf16 v[96:99], v[170:173], v[232:235], v[96:99]
	v_mfma_f32_16x16x32_bf16 v[80:83], v[170:173], v[240:243], v[80:83]
	v_mfma_f32_16x16x32_bf16 v[84:87], v[150:153], v[240:243], v[84:87]
	s_setprio 0
	s_setprio 1
	v_mfma_f32_16x16x32_bf16 v[108:111], v[178:181], v[212:215], v[108:111]
	v_mfma_f32_16x16x32_bf16 v[104:107], v[186:189], v[212:215], v[104:107]
	v_mfma_f32_16x16x32_bf16 v[88:91], v[186:189], v[220:223], v[88:91]
	v_mfma_f32_16x16x32_bf16 v[92:95], v[178:181], v[220:223], v[92:95]
	v_mfma_f32_16x16x32_bf16 v[76:79], v[178:181], v[228:231], v[76:79]
	v_mfma_f32_16x16x32_bf16 v[72:75], v[186:189], v[228:231], v[72:75]
	v_mfma_f32_16x16x32_bf16 v[64:67], v[186:189], v[236:239], v[64:67]
	v_mfma_f32_16x16x32_bf16 v[68:71], v[178:181], v[236:239], v[68:71]
	v_mfma_f32_16x16x32_bf16 v[108:111], v[182:185], v[216:219], v[108:111]
	v_mfma_f32_16x16x32_bf16 v[104:107], v[208:211], v[216:219], v[104:107]
	v_mfma_f32_16x16x32_bf16 v[88:91], v[208:211], v[224:227], v[88:91]
	v_mfma_f32_16x16x32_bf16 v[92:95], v[182:185], v[224:227], v[92:95]
	v_mfma_f32_16x16x32_bf16 v[76:79], v[182:185], v[232:235], v[76:79]
	v_mfma_f32_16x16x32_bf16 v[72:75], v[208:211], v[232:235], v[72:75]
	v_mfma_f32_16x16x32_bf16 v[64:67], v[208:211], v[240:243], v[64:67]
	v_mfma_f32_16x16x32_bf16 v[68:71], v[182:185], v[240:243], v[68:71]
	s_setprio 0
	s_barrier
	s_add_i32 s39, s65, s52
	v_lshl_add_u64 v[158:159], s[44:45], 0, v[132:133]
	s_mov_b32 m0, s39
	ds_read_b128 v[212:215], v168 offset:16384
	ds_read_b128 v[216:219], v168 offset:17408
	ds_read_b128 v[220:223], v168 offset:18432
	ds_read_b128 v[224:227], v168 offset:19456
	ds_read_b128 v[228:231], v168 offset:20480
	ds_read_b128 v[232:235], v168 offset:21504
	ds_read_b128 v[236:239], v168 offset:22528
	ds_read_b128 v[240:243], v168 offset:23552
	global_load_lds_dwordx4 v[158:159], off
	s_add_i32 m0, s39, 0x2000
	s_add_u32 s66, s44, 0x10000
	v_lshl_add_u64 v[174:175], s[44:45], 0, v[128:129]
	s_addc_u32 s67, s45, 0
	s_add_i32 s37, s37, s52
	global_load_lds_dwordx4 v[174:175], off
	v_lshl_add_u64 v[244:245], s[66:67], 0, v[132:133]
	s_mov_b32 m0, s37
	v_lshl_add_u64 v[246:247], s[62:63], 0, v[130:131]
	global_load_lds_dwordx4 v[244:245], off
	v_lshl_add_u64 v[244:245], s[66:67], 0, v[128:129]
	s_add_i32 m0, s37, 0x2000
	s_nop 0
	global_load_lds_dwordx4 v[244:245], off
	v_lshl_add_u64 v[244:245], s[62:63], 0, v[134:135]
	s_mov_b32 m0, s56
	s_nop 0
	global_load_lds_dwordx4 v[244:245], off
	s_mov_b32 m0, s57
	s_nop 0
	global_load_lds_dwordx4 v[246:247], off
	s_waitcnt vmcnt(8)
	s_waitcnt lgkmcnt(0)
	s_barrier
	s_setprio 1
	s_waitcnt lgkmcnt(0)
	v_mfma_f32_16x16x32_bf16 v[60:63], v[146:149], v[212:215], v[60:63]
	v_mfma_f32_16x16x32_bf16 v[56:59], v[154:157], v[212:215], v[56:59]
	v_mfma_f32_16x16x32_bf16 v[48:51], v[154:157], v[220:223], v[48:51]
	v_mfma_f32_16x16x32_bf16 v[52:55], v[146:149], v[220:223], v[52:55]
	v_mfma_f32_16x16x32_bf16 v[36:39], v[146:149], v[228:231], v[36:39]
	v_mfma_f32_16x16x32_bf16 v[32:35], v[154:157], v[228:231], v[32:35]
	v_mfma_f32_16x16x32_bf16 v[16:19], v[154:157], v[236:239], v[16:19]
	v_mfma_f32_16x16x32_bf16 v[20:23], v[146:149], v[236:239], v[20:23]
	v_mfma_f32_16x16x32_bf16 v[60:63], v[150:153], v[216:219], v[60:63]
	v_mfma_f32_16x16x32_bf16 v[56:59], v[170:173], v[216:219], v[56:59]
	v_mfma_f32_16x16x32_bf16 v[48:51], v[170:173], v[224:227], v[48:51]
	v_mfma_f32_16x16x32_bf16 v[52:55], v[150:153], v[224:227], v[52:55]
	v_mfma_f32_16x16x32_bf16 v[36:39], v[150:153], v[232:235], v[36:39]
	v_mfma_f32_16x16x32_bf16 v[32:35], v[170:173], v[232:235], v[32:35]
	v_mfma_f32_16x16x32_bf16 v[16:19], v[170:173], v[240:243], v[16:19]
	v_mfma_f32_16x16x32_bf16 v[20:23], v[150:153], v[240:243], v[20:23]
	s_setprio 0
	s_setprio 1
	v_mfma_f32_16x16x32_bf16 v[44:47], v[178:181], v[212:215], v[44:47]
	v_mfma_f32_16x16x32_bf16 v[40:43], v[186:189], v[212:215], v[40:43]
	v_mfma_f32_16x16x32_bf16 v[24:27], v[186:189], v[220:223], v[24:27]
	v_mfma_f32_16x16x32_bf16 v[28:31], v[178:181], v[220:223], v[28:31]
	v_mfma_f32_16x16x32_bf16 v[12:15], v[178:181], v[228:231], v[12:15]
	v_mfma_f32_16x16x32_bf16 v[8:11], v[186:189], v[228:231], v[8:11]
	v_mfma_f32_16x16x32_bf16 v[0:3], v[186:189], v[236:239], v[0:3]
	v_mfma_f32_16x16x32_bf16 v[4:7], v[178:181], v[236:239], v[4:7]
	v_mfma_f32_16x16x32_bf16 v[44:47], v[182:185], v[216:219], v[44:47]
	v_mfma_f32_16x16x32_bf16 v[40:43], v[208:211], v[216:219], v[40:43]
	v_mfma_f32_16x16x32_bf16 v[24:27], v[208:211], v[224:227], v[24:27]
	v_mfma_f32_16x16x32_bf16 v[28:31], v[182:185], v[224:227], v[28:31]
	v_mfma_f32_16x16x32_bf16 v[12:15], v[182:185], v[232:235], v[12:15]
	v_mfma_f32_16x16x32_bf16 v[8:11], v[208:211], v[232:235], v[8:11]
	v_mfma_f32_16x16x32_bf16 v[0:3], v[208:211], v[240:243], v[0:3]
	v_mfma_f32_16x16x32_bf16 v[4:7], v[182:185], v[240:243], v[4:7]
	s_setprio 0
	s_barrier
	s_add_i32 s37, 0, 0x18000
	v_add_u32_e32 v145, s37, v162
	s_add_i32 s39, 0, 0x1c000
	ds_read_b128 v[146:149], v145
	ds_read_b128 v[150:153], v145 offset:1024
	ds_read_b128 v[154:157], v145 offset:2048
	ds_read_b128 v[170:173], v145 offset:3072
	v_add_u32_e32 v145, s39, v162
	ds_read_b128 v[178:181], v145
	ds_read_b128 v[182:185], v145 offset:1024
	ds_read_b128 v[186:189], v145 offset:2048
	ds_read_b128 v[208:211], v145 offset:3072
	s_add_u32 s62, s62, 0x40000
	s_addc_u32 s63, s63, 0
	s_mov_b32 m0, s54
	v_lshl_add_u64 v[248:249], s[62:63], 0, v[134:135]
	ds_read_b128 v[212:215], v168 offset:32768
	ds_read_b128 v[216:219], v168 offset:33792
	ds_read_b128 v[220:223], v168 offset:34816
	ds_read_b128 v[224:227], v168 offset:35840
	ds_read_b128 v[228:231], v168 offset:36864
	ds_read_b128 v[232:235], v168 offset:37888
	ds_read_b128 v[236:239], v168 offset:38912
	ds_read_b128 v[240:243], v168 offset:39936
	global_load_lds_dwordx4 v[248:249], off
	v_lshl_add_u64 v[248:249], s[62:63], 0, v[130:131]
	s_mov_b32 m0, s55
	s_nop 0
	global_load_lds_dwordx4 v[248:249], off
	s_waitcnt vmcnt(8)
	s_waitcnt lgkmcnt(0)
	s_barrier
	s_setprio 1
	s_waitcnt lgkmcnt(0)
	v_mfma_f32_16x16x32_bf16 v[124:127], v[146:149], v[212:215], v[124:127]
	v_mfma_f32_16x16x32_bf16 v[120:123], v[154:157], v[212:215], v[120:123]
	v_mfma_f32_16x16x32_bf16 v[112:115], v[154:157], v[220:223], v[112:115]
	v_mfma_f32_16x16x32_bf16 v[116:119], v[146:149], v[220:223], v[116:119]
	v_mfma_f32_16x16x32_bf16 v[100:103], v[146:149], v[228:231], v[100:103]
	v_mfma_f32_16x16x32_bf16 v[96:99], v[154:157], v[228:231], v[96:99]
	v_mfma_f32_16x16x32_bf16 v[80:83], v[154:157], v[236:239], v[80:83]
	v_mfma_f32_16x16x32_bf16 v[84:87], v[146:149], v[236:239], v[84:87]
	v_mfma_f32_16x16x32_bf16 v[124:127], v[150:153], v[216:219], v[124:127]
	v_mfma_f32_16x16x32_bf16 v[120:123], v[170:173], v[216:219], v[120:123]
	v_mfma_f32_16x16x32_bf16 v[112:115], v[170:173], v[224:227], v[112:115]
	v_mfma_f32_16x16x32_bf16 v[116:119], v[150:153], v[224:227], v[116:119]
	v_mfma_f32_16x16x32_bf16 v[100:103], v[150:153], v[232:235], v[100:103]
	v_mfma_f32_16x16x32_bf16 v[96:99], v[170:173], v[232:235], v[96:99]
	v_mfma_f32_16x16x32_bf16 v[80:83], v[170:173], v[240:243], v[80:83]
	v_mfma_f32_16x16x32_bf16 v[84:87], v[150:153], v[240:243], v[84:87]
	s_setprio 0
	s_setprio 1
	v_mfma_f32_16x16x32_bf16 v[108:111], v[178:181], v[212:215], v[108:111]
	v_mfma_f32_16x16x32_bf16 v[104:107], v[186:189], v[212:215], v[104:107]
	v_mfma_f32_16x16x32_bf16 v[88:91], v[186:189], v[220:223], v[88:91]
	v_mfma_f32_16x16x32_bf16 v[92:95], v[178:181], v[220:223], v[92:95]
	v_mfma_f32_16x16x32_bf16 v[76:79], v[178:181], v[228:231], v[76:79]
	v_mfma_f32_16x16x32_bf16 v[72:75], v[186:189], v[228:231], v[72:75]
	v_mfma_f32_16x16x32_bf16 v[64:67], v[186:189], v[236:239], v[64:67]
	v_mfma_f32_16x16x32_bf16 v[68:71], v[178:181], v[236:239], v[68:71]
	v_mfma_f32_16x16x32_bf16 v[108:111], v[182:185], v[216:219], v[108:111]
	v_mfma_f32_16x16x32_bf16 v[104:107], v[208:211], v[216:219], v[104:107]
	v_mfma_f32_16x16x32_bf16 v[88:91], v[208:211], v[224:227], v[88:91]
	v_mfma_f32_16x16x32_bf16 v[92:95], v[182:185], v[224:227], v[92:95]
	v_mfma_f32_16x16x32_bf16 v[76:79], v[182:185], v[232:235], v[76:79]
	v_mfma_f32_16x16x32_bf16 v[72:75], v[208:211], v[232:235], v[72:75]
	v_mfma_f32_16x16x32_bf16 v[64:67], v[208:211], v[240:243], v[64:67]
	v_mfma_f32_16x16x32_bf16 v[68:71], v[182:185], v[240:243], v[68:71]
	s_setprio 0
	s_barrier
	s_add_i32 s37, s37, s52
	v_lshl_add_u64 v[158:159], v[158:159], 0, s[26:27]
	s_mov_b32 m0, s37
	ds_read_b128 v[212:215], v168 offset:49152
	ds_read_b128 v[216:219], v168 offset:50176
	ds_read_b128 v[220:223], v168 offset:51200
	ds_read_b128 v[224:227], v168 offset:52224
	ds_read_b128 v[228:231], v168 offset:53248
	ds_read_b128 v[232:235], v168 offset:54272
	ds_read_b128 v[236:239], v168 offset:55296
	ds_read_b128 v[240:243], v168 offset:56320
	global_load_lds_dwordx4 v[158:159], off
	s_add_i32 m0, s37, 0x2000
	s_add_u32 s44, s44, 0x10080
	v_lshl_add_u64 v[158:159], v[174:175], 0, s[26:27]
	s_addc_u32 s45, s45, 0
	s_add_i32 s37, s39, s52
	global_load_lds_dwordx4 v[158:159], off
	v_lshl_add_u64 v[158:159], s[44:45], 0, v[132:133]
	s_mov_b32 m0, s37
	s_nop 0
	global_load_lds_dwordx4 v[158:159], off
	v_lshl_add_u64 v[158:159], s[44:45], 0, v[128:129]
	s_add_i32 m0, s37, 0x2000
	s_nop 0
	global_load_lds_dwordx4 v[158:159], off
	v_lshl_add_u64 v[158:159], v[244:245], 0, s[26:27]
	s_mov_b32 m0, s34
	s_nop 0
	global_load_lds_dwordx4 v[158:159], off
	v_lshl_add_u64 v[158:159], v[246:247], 0, s[26:27]
	s_mov_b32 m0, s53
	s_nop 0
	global_load_lds_dwordx4 v[158:159], off
	s_waitcnt vmcnt(8)
	s_waitcnt lgkmcnt(0)
	s_barrier
	s_setprio 1
	s_waitcnt lgkmcnt(0)
	v_mfma_f32_16x16x32_bf16 v[60:63], v[146:149], v[212:215], v[60:63]
	v_mfma_f32_16x16x32_bf16 v[56:59], v[154:157], v[212:215], v[56:59]
	v_mfma_f32_16x16x32_bf16 v[48:51], v[154:157], v[220:223], v[48:51]
	v_mfma_f32_16x16x32_bf16 v[52:55], v[146:149], v[220:223], v[52:55]
	v_mfma_f32_16x16x32_bf16 v[36:39], v[146:149], v[228:231], v[36:39]
	v_mfma_f32_16x16x32_bf16 v[32:35], v[154:157], v[228:231], v[32:35]
	v_mfma_f32_16x16x32_bf16 v[16:19], v[154:157], v[236:239], v[16:19]
	v_mfma_f32_16x16x32_bf16 v[20:23], v[146:149], v[236:239], v[20:23]
	v_mfma_f32_16x16x32_bf16 v[60:63], v[150:153], v[216:219], v[60:63]
	v_mfma_f32_16x16x32_bf16 v[56:59], v[170:173], v[216:219], v[56:59]
	v_mfma_f32_16x16x32_bf16 v[48:51], v[170:173], v[224:227], v[48:51]
	v_mfma_f32_16x16x32_bf16 v[52:55], v[150:153], v[224:227], v[52:55]
	v_mfma_f32_16x16x32_bf16 v[36:39], v[150:153], v[232:235], v[36:39]
	v_mfma_f32_16x16x32_bf16 v[32:35], v[170:173], v[232:235], v[32:35]
	v_mfma_f32_16x16x32_bf16 v[16:19], v[170:173], v[240:243], v[16:19]
	v_mfma_f32_16x16x32_bf16 v[20:23], v[150:153], v[240:243], v[20:23]
	s_setprio 0
	s_setprio 1
	v_mfma_f32_16x16x32_bf16 v[44:47], v[178:181], v[212:215], v[44:47]
	v_mfma_f32_16x16x32_bf16 v[40:43], v[186:189], v[212:215], v[40:43]
	v_mfma_f32_16x16x32_bf16 v[24:27], v[186:189], v[220:223], v[24:27]
	v_mfma_f32_16x16x32_bf16 v[28:31], v[178:181], v[220:223], v[28:31]
	v_mfma_f32_16x16x32_bf16 v[12:15], v[178:181], v[228:231], v[12:15]
	v_mfma_f32_16x16x32_bf16 v[8:11], v[186:189], v[228:231], v[8:11]
	v_mfma_f32_16x16x32_bf16 v[0:3], v[186:189], v[236:239], v[0:3]
	v_mfma_f32_16x16x32_bf16 v[4:7], v[178:181], v[236:239], v[4:7]
	v_mfma_f32_16x16x32_bf16 v[44:47], v[182:185], v[216:219], v[44:47]
	v_mfma_f32_16x16x32_bf16 v[40:43], v[208:211], v[216:219], v[40:43]
	v_mfma_f32_16x16x32_bf16 v[24:27], v[208:211], v[224:227], v[24:27]
	v_mfma_f32_16x16x32_bf16 v[28:31], v[182:185], v[224:227], v[28:31]
	v_mfma_f32_16x16x32_bf16 v[12:15], v[182:185], v[232:235], v[12:15]
	v_mfma_f32_16x16x32_bf16 v[8:11], v[208:211], v[232:235], v[8:11]
	v_mfma_f32_16x16x32_bf16 v[0:3], v[208:211], v[240:243], v[0:3]
	v_mfma_f32_16x16x32_bf16 v[4:7], v[182:185], v[240:243], v[4:7]
	s_setprio 0
	s_barrier
	s_add_i32 s64, s64, 2
	s_add_u32 s42, s42, 0x100
	s_addc_u32 s43, s43, 0
	s_add_u32 s22, s22, 0x100
	s_addc_u32 s30, s30, 0
	s_cmp_gt_u32 s64, 13
	s_cbranch_scc0 .LBB0_645
	v_readlane_b32 s0, v252, 26
	v_readlane_b32 s1, v252, 27
	s_and_b64 vcc, exec, s[0:1]
	v_readlane_b32 s68, v252, 11
	v_readlane_b32 s69, v252, 12
	s_cbranch_vccz .LBB0_648
	s_barrier

.LBB0_1180:
	s_add_u32 s37, s42, 0xfffc0080
	s_addc_u32 s39, s43, -1
	s_add_i32 s65, 0, 0x10000
	s_cmp_eq_u32 s64, 12
	s_cselect_b32 s63, s0, s39
	s_cselect_b32 s62, s1, s37
	v_add_u32_e32 v145, s65, v162
	s_cselect_b32 s45, s20, s30
	s_cselect_b32 s44, s21, s22
	s_add_i32 s37, 0, 0x14000
	ds_read_b128 v[146:149], v145
	ds_read_b128 v[150:153], v145 offset:1024
	ds_read_b128 v[154:157], v145 offset:2048
	ds_read_b128 v[170:173], v145 offset:3072
	v_add_u32_e32 v145, s37, v162
	ds_read_b128 v[178:181], v145
	ds_read_b128 v[182:185], v145 offset:1024
	ds_read_b128 v[186:189], v145 offset:2048
	ds_read_b128 v[208:211], v145 offset:3072
	v_lshl_add_u64 v[158:159], s[42:43], 0, v[140:141]
	s_add_i32 m0, s56, 0xc000
	ds_read_b128 v[212:215], v168
	ds_read_b128 v[216:219], v168 offset:1024
	ds_read_b128 v[220:223], v168 offset:2048
	ds_read_b128 v[224:227], v168 offset:3072
	ds_read_b128 v[228:231], v168 offset:4096
	ds_read_b128 v[232:235], v168 offset:5120
	ds_read_b128 v[236:239], v168 offset:6144
	ds_read_b128 v[240:243], v168 offset:7168
	global_load_lds_dwordx4 v[158:159], off
	v_lshl_add_u64 v[158:159], s[42:43], 0, v[142:143]
	s_add_i32 m0, s56, 0xe000
	s_nop 0
	global_load_lds_dwordx4 v[158:159], off
	s_waitcnt vmcnt(8)
	s_waitcnt lgkmcnt(0)
	s_barrier
	s_setprio 1
	s_waitcnt lgkmcnt(0)
	v_mfma_f32_16x16x32_bf16 v[124:127], v[146:149], v[212:215], v[124:127]
	v_mfma_f32_16x16x32_bf16 v[120:123], v[154:157], v[212:215], v[120:123]
	v_mfma_f32_16x16x32_bf16 v[112:115], v[154:157], v[220:223], v[112:115]
	v_mfma_f32_16x16x32_bf16 v[116:119], v[146:149], v[220:223], v[116:119]
	v_mfma_f32_16x16x32_bf16 v[100:103], v[146:149], v[228:231], v[100:103]
	v_mfma_f32_16x16x32_bf16 v[96:99], v[154:157], v[228:231], v[96:99]
	v_mfma_f32_16x16x32_bf16 v[80:83], v[154:157], v[236:239], v[80:83]
	v_mfma_f32_16x16x32_bf16 v[84:87], v[146:149], v[236:239], v[84:87]
	v_mfma_f32_16x16x32_bf16 v[124:127], v[150:153], v[216:219], v[124:127]
	v_mfma_f32_16x16x32_bf16 v[120:123], v[170:173], v[216:219], v[120:123]
	v_mfma_f32_16x16x32_bf16 v[112:115], v[170:173], v[224:227], v[112:115]
	v_mfma_f32_16x16x32_bf16 v[116:119], v[150:153], v[224:227], v[116:119]
	v_mfma_f32_16x16x32_bf16 v[100:103], v[150:153], v[232:235], v[100:103]
	v_mfma_f32_16x16x32_bf16 v[96:99], v[170:173], v[232:235], v[96:99]
	v_mfma_f32_16x16x32_bf16 v[80:83], v[170:173], v[240:243], v[80:83]
	v_mfma_f32_16x16x32_bf16 v[84:87], v[150:153], v[240:243], v[84:87]
	s_setprio 0
	s_setprio 1
	v_mfma_f32_16x16x32_bf16 v[108:111], v[178:181], v[212:215], v[108:111]
	v_mfma_f32_16x16x32_bf16 v[104:107], v[186:189], v[212:215], v[104:107]
	v_mfma_f32_16x16x32_bf16 v[88:91], v[186:189], v[220:223], v[88:91]
	v_mfma_f32_16x16x32_bf16 v[92:95], v[178:181], v[220:223], v[92:95]
	v_mfma_f32_16x16x32_bf16 v[76:79], v[178:181], v[228:231], v[76:79]
	v_mfma_f32_16x16x32_bf16 v[72:75], v[186:189], v[228:231], v[72:75]
	v_mfma_f32_16x16x32_bf16 v[64:67], v[186:189], v[236:239], v[64:67]
	v_mfma_f32_16x16x32_bf16 v[68:71], v[178:181], v[236:239], v[68:71]
	v_mfma_f32_16x16x32_bf16 v[108:111], v[182:185], v[216:219], v[108:111]
	v_mfma_f32_16x16x32_bf16 v[104:107], v[208:211], v[216:219], v[104:107]
	v_mfma_f32_16x16x32_bf16 v[88:91], v[208:211], v[224:227], v[88:91]
	v_mfma_f32_16x16x32_bf16 v[92:95], v[182:185], v[224:227], v[92:95]
	v_mfma_f32_16x16x32_bf16 v[76:79], v[182:185], v[232:235], v[76:79]
	v_mfma_f32_16x16x32_bf16 v[72:75], v[208:211], v[232:235], v[72:75]
	v_mfma_f32_16x16x32_bf16 v[64:67], v[208:211], v[240:243], v[64:67]
	v_mfma_f32_16x16x32_bf16 v[68:71], v[182:185], v[240:243], v[68:71]
	s_setprio 0
	s_barrier
	s_add_i32 s39, s65, s52
	v_lshl_add_u64 v[158:159], s[44:45], 0, v[132:133]
	s_mov_b32 m0, s39
	ds_read_b128 v[212:215], v168 offset:16384
	ds_read_b128 v[216:219], v168 offset:17408
	ds_read_b128 v[220:223], v168 offset:18432
	ds_read_b128 v[224:227], v168 offset:19456
	ds_read_b128 v[228:231], v168 offset:20480
	ds_read_b128 v[232:235], v168 offset:21504
	ds_read_b128 v[236:239], v168 offset:22528
	ds_read_b128 v[240:243], v168 offset:23552
	global_load_lds_dwordx4 v[158:159], off
	s_add_i32 m0, s39, 0x2000
	s_add_u32 s66, s44, 0x10000
	v_lshl_add_u64 v[174:175], s[44:45], 0, v[128:129]
	s_addc_u32 s67, s45, 0
	s_add_i32 s37, s37, s52
	global_load_lds_dwordx4 v[174:175], off
	v_lshl_add_u64 v[244:245], s[66:67], 0, v[132:133]
	s_mov_b32 m0, s37
	v_lshl_add_u64 v[246:247], s[62:63], 0, v[130:131]
	global_load_lds_dwordx4 v[244:245], off
	v_lshl_add_u64 v[244:245], s[66:67], 0, v[128:129]
	s_add_i32 m0, s37, 0x2000
	s_nop 0
	global_load_lds_dwordx4 v[244:245], off
	v_lshl_add_u64 v[244:245], s[62:63], 0, v[134:135]
	s_mov_b32 m0, s56
	s_nop 0
	global_load_lds_dwordx4 v[244:245], off
	s_mov_b32 m0, s57
	s_nop 0
	global_load_lds_dwordx4 v[246:247], off
	s_waitcnt vmcnt(8)
	s_waitcnt lgkmcnt(0)
	s_barrier
	s_setprio 1
	s_waitcnt lgkmcnt(0)
	v_mfma_f32_16x16x32_bf16 v[60:63], v[146:149], v[212:215], v[60:63]
	v_mfma_f32_16x16x32_bf16 v[56:59], v[154:157], v[212:215], v[56:59]
	v_mfma_f32_16x16x32_bf16 v[48:51], v[154:157], v[220:223], v[48:51]
	v_mfma_f32_16x16x32_bf16 v[52:55], v[146:149], v[220:223], v[52:55]
	v_mfma_f32_16x16x32_bf16 v[36:39], v[146:149], v[228:231], v[36:39]
	v_mfma_f32_16x16x32_bf16 v[32:35], v[154:157], v[228:231], v[32:35]
	v_mfma_f32_16x16x32_bf16 v[16:19], v[154:157], v[236:239], v[16:19]
	v_mfma_f32_16x16x32_bf16 v[20:23], v[146:149], v[236:239], v[20:23]
	v_mfma_f32_16x16x32_bf16 v[60:63], v[150:153], v[216:219], v[60:63]
	v_mfma_f32_16x16x32_bf16 v[56:59], v[170:173], v[216:219], v[56:59]
	v_mfma_f32_16x16x32_bf16 v[48:51], v[170:173], v[224:227], v[48:51]
	v_mfma_f32_16x16x32_bf16 v[52:55], v[150:153], v[224:227], v[52:55]
	v_mfma_f32_16x16x32_bf16 v[36:39], v[150:153], v[232:235], v[36:39]
	v_mfma_f32_16x16x32_bf16 v[32:35], v[170:173], v[232:235], v[32:35]
	v_mfma_f32_16x16x32_bf16 v[16:19], v[170:173], v[240:243], v[16:19]
	v_mfma_f32_16x16x32_bf16 v[20:23], v[150:153], v[240:243], v[20:23]
	s_setprio 0
	s_setprio 1
	v_mfma_f32_16x16x32_bf16 v[44:47], v[178:181], v[212:215], v[44:47]
	v_mfma_f32_16x16x32_bf16 v[40:43], v[186:189], v[212:215], v[40:43]
	v_mfma_f32_16x16x32_bf16 v[24:27], v[186:189], v[220:223], v[24:27]
	v_mfma_f32_16x16x32_bf16 v[28:31], v[178:181], v[220:223], v[28:31]
	v_mfma_f32_16x16x32_bf16 v[12:15], v[178:181], v[228:231], v[12:15]
	v_mfma_f32_16x16x32_bf16 v[8:11], v[186:189], v[228:231], v[8:11]
	v_mfma_f32_16x16x32_bf16 v[0:3], v[186:189], v[236:239], v[0:3]
	v_mfma_f32_16x16x32_bf16 v[4:7], v[178:181], v[236:239], v[4:7]
	v_mfma_f32_16x16x32_bf16 v[44:47], v[182:185], v[216:219], v[44:47]
	v_mfma_f32_16x16x32_bf16 v[40:43], v[208:211], v[216:219], v[40:43]
	v_mfma_f32_16x16x32_bf16 v[24:27], v[208:211], v[224:227], v[24:27]
	v_mfma_f32_16x16x32_bf16 v[28:31], v[182:185], v[224:227], v[28:31]
	v_mfma_f32_16x16x32_bf16 v[12:15], v[182:185], v[232:235], v[12:15]
	v_mfma_f32_16x16x32_bf16 v[8:11], v[208:211], v[232:235], v[8:11]
	v_mfma_f32_16x16x32_bf16 v[0:3], v[208:211], v[240:243], v[0:3]
	v_mfma_f32_16x16x32_bf16 v[4:7], v[182:185], v[240:243], v[4:7]
	s_setprio 0
	s_barrier
	s_add_i32 s37, 0, 0x18000
	v_add_u32_e32 v145, s37, v162
	s_add_i32 s39, 0, 0x1c000
	ds_read_b128 v[146:149], v145
	ds_read_b128 v[150:153], v145 offset:1024
	ds_read_b128 v[154:157], v145 offset:2048
	ds_read_b128 v[170:173], v145 offset:3072
	v_add_u32_e32 v145, s39, v162
	ds_read_b128 v[178:181], v145
	ds_read_b128 v[182:185], v145 offset:1024
	ds_read_b128 v[186:189], v145 offset:2048
	ds_read_b128 v[208:211], v145 offset:3072
	s_add_u32 s62, s62, 0x40000
	s_addc_u32 s63, s63, 0
	s_mov_b32 m0, s54
	v_lshl_add_u64 v[248:249], s[62:63], 0, v[134:135]
	ds_read_b128 v[212:215], v168 offset:32768
	ds_read_b128 v[216:219], v168 offset:33792
	ds_read_b128 v[220:223], v168 offset:34816
	ds_read_b128 v[224:227], v168 offset:35840
	ds_read_b128 v[228:231], v168 offset:36864
	ds_read_b128 v[232:235], v168 offset:37888
	ds_read_b128 v[236:239], v168 offset:38912
	ds_read_b128 v[240:243], v168 offset:39936
	global_load_lds_dwordx4 v[248:249], off
	v_lshl_add_u64 v[248:249], s[62:63], 0, v[130:131]
	s_mov_b32 m0, s55
	s_nop 0
	global_load_lds_dwordx4 v[248:249], off
	s_waitcnt vmcnt(8)
	s_waitcnt lgkmcnt(0)
	s_barrier
	s_setprio 1
	s_waitcnt lgkmcnt(0)
	v_mfma_f32_16x16x32_bf16 v[124:127], v[146:149], v[212:215], v[124:127]
	v_mfma_f32_16x16x32_bf16 v[120:123], v[154:157], v[212:215], v[120:123]
	v_mfma_f32_16x16x32_bf16 v[112:115], v[154:157], v[220:223], v[112:115]
	v_mfma_f32_16x16x32_bf16 v[116:119], v[146:149], v[220:223], v[116:119]
	v_mfma_f32_16x16x32_bf16 v[100:103], v[146:149], v[228:231], v[100:103]
	v_mfma_f32_16x16x32_bf16 v[96:99], v[154:157], v[228:231], v[96:99]
	v_mfma_f32_16x16x32_bf16 v[80:83], v[154:157], v[236:239], v[80:83]
	v_mfma_f32_16x16x32_bf16 v[84:87], v[146:149], v[236:239], v[84:87]
	v_mfma_f32_16x16x32_bf16 v[124:127], v[150:153], v[216:219], v[124:127]
	v_mfma_f32_16x16x32_bf16 v[120:123], v[170:173], v[216:219], v[120:123]
	v_mfma_f32_16x16x32_bf16 v[112:115], v[170:173], v[224:227], v[112:115]
	v_mfma_f32_16x16x32_bf16 v[116:119], v[150:153], v[224:227], v[116:119]
	v_mfma_f32_16x16x32_bf16 v[100:103], v[150:153], v[232:235], v[100:103]
	v_mfma_f32_16x16x32_bf16 v[96:99], v[170:173], v[232:235], v[96:99]
	v_mfma_f32_16x16x32_bf16 v[80:83], v[170:173], v[240:243], v[80:83]
	v_mfma_f32_16x16x32_bf16 v[84:87], v[150:153], v[240:243], v[84:87]
	s_setprio 0
	s_setprio 1
	v_mfma_f32_16x16x32_bf16 v[108:111], v[178:181], v[212:215], v[108:111]
	v_mfma_f32_16x16x32_bf16 v[104:107], v[186:189], v[212:215], v[104:107]
	v_mfma_f32_16x16x32_bf16 v[88:91], v[186:189], v[220:223], v[88:91]
	v_mfma_f32_16x16x32_bf16 v[92:95], v[178:181], v[220:223], v[92:95]
	v_mfma_f32_16x16x32_bf16 v[76:79], v[178:181], v[228:231], v[76:79]
	v_mfma_f32_16x16x32_bf16 v[72:75], v[186:189], v[228:231], v[72:75]
	v_mfma_f32_16x16x32_bf16 v[64:67], v[186:189], v[236:239], v[64:67]
	v_mfma_f32_16x16x32_bf16 v[68:71], v[178:181], v[236:239], v[68:71]
	v_mfma_f32_16x16x32_bf16 v[108:111], v[182:185], v[216:219], v[108:111]
	v_mfma_f32_16x16x32_bf16 v[104:107], v[208:211], v[216:219], v[104:107]
	v_mfma_f32_16x16x32_bf16 v[88:91], v[208:211], v[224:227], v[88:91]
	v_mfma_f32_16x16x32_bf16 v[92:95], v[182:185], v[224:227], v[92:95]
	v_mfma_f32_16x16x32_bf16 v[76:79], v[182:185], v[232:235], v[76:79]
	v_mfma_f32_16x16x32_bf16 v[72:75], v[208:211], v[232:235], v[72:75]
	v_mfma_f32_16x16x32_bf16 v[64:67], v[208:211], v[240:243], v[64:67]
	v_mfma_f32_16x16x32_bf16 v[68:71], v[182:185], v[240:243], v[68:71]
	s_setprio 0
	s_barrier
	s_add_i32 s37, s37, s52
	v_lshl_add_u64 v[158:159], v[158:159], 0, s[26:27]
	s_mov_b32 m0, s37
	ds_read_b128 v[212:215], v168 offset:49152
	ds_read_b128 v[216:219], v168 offset:50176
	ds_read_b128 v[220:223], v168 offset:51200
	ds_read_b128 v[224:227], v168 offset:52224
	ds_read_b128 v[228:231], v168 offset:53248
	ds_read_b128 v[232:235], v168 offset:54272
	ds_read_b128 v[236:239], v168 offset:55296
	ds_read_b128 v[240:243], v168 offset:56320
	global_load_lds_dwordx4 v[158:159], off
	s_add_i32 m0, s37, 0x2000
	s_add_u32 s44, s44, 0x10080
	v_lshl_add_u64 v[158:159], v[174:175], 0, s[26:27]
	s_addc_u32 s45, s45, 0
	s_add_i32 s37, s39, s52
	global_load_lds_dwordx4 v[158:159], off
	v_lshl_add_u64 v[158:159], s[44:45], 0, v[132:133]
	s_mov_b32 m0, s37
	s_nop 0
	global_load_lds_dwordx4 v[158:159], off
	v_lshl_add_u64 v[158:159], s[44:45], 0, v[128:129]
	s_add_i32 m0, s37, 0x2000
	s_nop 0
	global_load_lds_dwordx4 v[158:159], off
	v_lshl_add_u64 v[158:159], v[244:245], 0, s[26:27]
	s_mov_b32 m0, s35
	s_nop 0
	global_load_lds_dwordx4 v[158:159], off
	v_lshl_add_u64 v[158:159], v[246:247], 0, s[26:27]
	s_mov_b32 m0, s53
	s_nop 0
	global_load_lds_dwordx4 v[158:159], off
	s_waitcnt vmcnt(8)
	s_waitcnt lgkmcnt(0)
	s_barrier
	s_setprio 1
	s_waitcnt lgkmcnt(0)
	v_mfma_f32_16x16x32_bf16 v[60:63], v[146:149], v[212:215], v[60:63]
	v_mfma_f32_16x16x32_bf16 v[56:59], v[154:157], v[212:215], v[56:59]
	v_mfma_f32_16x16x32_bf16 v[48:51], v[154:157], v[220:223], v[48:51]
	v_mfma_f32_16x16x32_bf16 v[52:55], v[146:149], v[220:223], v[52:55]
	v_mfma_f32_16x16x32_bf16 v[36:39], v[146:149], v[228:231], v[36:39]
	v_mfma_f32_16x16x32_bf16 v[32:35], v[154:157], v[228:231], v[32:35]
	v_mfma_f32_16x16x32_bf16 v[16:19], v[154:157], v[236:239], v[16:19]
	v_mfma_f32_16x16x32_bf16 v[20:23], v[146:149], v[236:239], v[20:23]
	v_mfma_f32_16x16x32_bf16 v[60:63], v[150:153], v[216:219], v[60:63]
	v_mfma_f32_16x16x32_bf16 v[56:59], v[170:173], v[216:219], v[56:59]
	v_mfma_f32_16x16x32_bf16 v[48:51], v[170:173], v[224:227], v[48:51]
	v_mfma_f32_16x16x32_bf16 v[52:55], v[150:153], v[224:227], v[52:55]
	v_mfma_f32_16x16x32_bf16 v[36:39], v[150:153], v[232:235], v[36:39]
	v_mfma_f32_16x16x32_bf16 v[32:35], v[170:173], v[232:235], v[32:35]
	v_mfma_f32_16x16x32_bf16 v[16:19], v[170:173], v[240:243], v[16:19]
	v_mfma_f32_16x16x32_bf16 v[20:23], v[150:153], v[240:243], v[20:23]
	s_setprio 0
	s_setprio 1
	v_mfma_f32_16x16x32_bf16 v[44:47], v[178:181], v[212:215], v[44:47]
	v_mfma_f32_16x16x32_bf16 v[40:43], v[186:189], v[212:215], v[40:43]
	v_mfma_f32_16x16x32_bf16 v[24:27], v[186:189], v[220:223], v[24:27]
	v_mfma_f32_16x16x32_bf16 v[28:31], v[178:181], v[220:223], v[28:31]
	v_mfma_f32_16x16x32_bf16 v[12:15], v[178:181], v[228:231], v[12:15]
	v_mfma_f32_16x16x32_bf16 v[8:11], v[186:189], v[228:231], v[8:11]
	v_mfma_f32_16x16x32_bf16 v[0:3], v[186:189], v[236:239], v[0:3]
	v_mfma_f32_16x16x32_bf16 v[4:7], v[178:181], v[236:239], v[4:7]
	v_mfma_f32_16x16x32_bf16 v[44:47], v[182:185], v[216:219], v[44:47]
	v_mfma_f32_16x16x32_bf16 v[40:43], v[208:211], v[216:219], v[40:43]
	v_mfma_f32_16x16x32_bf16 v[24:27], v[208:211], v[224:227], v[24:27]
	v_mfma_f32_16x16x32_bf16 v[28:31], v[182:185], v[224:227], v[28:31]
	v_mfma_f32_16x16x32_bf16 v[12:15], v[182:185], v[232:235], v[12:15]
	v_mfma_f32_16x16x32_bf16 v[8:11], v[208:211], v[232:235], v[8:11]
	v_mfma_f32_16x16x32_bf16 v[0:3], v[208:211], v[240:243], v[0:3]
	v_mfma_f32_16x16x32_bf16 v[4:7], v[182:185], v[240:243], v[4:7]
	s_setprio 0
	s_barrier
	s_add_i32 s64, s64, 2
	s_add_u32 s42, s42, 0x100
	s_addc_u32 s43, s43, 0
	s_add_u32 s22, s22, 0x100
	s_addc_u32 s30, s30, 0
	s_cmp_gt_u32 s64, 13
	s_cbranch_scc0 .LBB0_1180
	v_readlane_b32 s0, v252, 26
	v_readlane_b32 s1, v252, 27
	s_and_b64 vcc, exec, s[0:1]
	v_readlane_b32 s68, v252, 11
	v_readlane_b32 s69, v252, 12
	s_cbranch_vccz .LBB0_1183
	s_barrier

.LBB0_1251:
	s_add_u32 s56, s54, 0x100
	s_addc_u32 s57, s55, 0
	s_add_i32 s34, 0, 0x10000
	s_cmp_eq_u32 s49, 40
	s_cselect_b32 s61, s20, s57
	s_cselect_b32 s60, s21, s56
	s_cselect_b32 s59, s70, s48
	s_cselect_b32 s58, vcc_lo, vcc_hi
	s_add_i32 s37, 0, 0x14000
	v_add_u32_e32 v168, s34, v178
	v_add_u32_e32 v188, s37, v178
	ds_read_b128 v[128:131], v168
	ds_read_b128 v[132:135], v168 offset:1024
	ds_read_b128 v[164:167], v168 offset:2048
	ds_read_b128 v[168:171], v168 offset:3072
	ds_read_b128 v[172:175], v188
	ds_read_b128 v[180:183], v188 offset:1024
	ds_read_b128 v[184:187], v188 offset:2048
	ds_read_b128 v[208:211], v188 offset:3072
	v_lshl_add_u64 v[188:189], s[54:55], 0, v[160:161]
	s_add_i32 m0, s62, 0xc000
	ds_read_b128 v[212:215], v179
	ds_read_b128 v[216:219], v179 offset:1024
	ds_read_b128 v[220:223], v179 offset:2048
	ds_read_b128 v[224:227], v179 offset:3072
	ds_read_b128 v[228:231], v179 offset:4096
	ds_read_b128 v[232:235], v179 offset:5120
	ds_read_b128 v[236:239], v179 offset:6144
	ds_read_b128 v[240:243], v179 offset:7168
	global_load_lds_dwordx4 v[188:189], off
	v_lshl_add_u64 v[188:189], s[54:55], 0, v[162:163]
	s_add_i32 m0, s62, 0xe000
	s_nop 0
	global_load_lds_dwordx4 v[188:189], off
	s_waitcnt vmcnt(8)
	s_waitcnt lgkmcnt(0)
	s_barrier
	s_setprio 1
	s_waitcnt lgkmcnt(0)
	v_mfma_f32_16x16x32_bf16 v[124:127], v[128:131], v[212:215], v[124:127]
	v_mfma_f32_16x16x32_bf16 v[120:123], v[164:167], v[212:215], v[120:123]
	v_mfma_f32_16x16x32_bf16 v[112:115], v[164:167], v[220:223], v[112:115]
	v_mfma_f32_16x16x32_bf16 v[116:119], v[128:131], v[220:223], v[116:119]
	v_mfma_f32_16x16x32_bf16 v[108:111], v[128:131], v[228:231], v[108:111]
	v_mfma_f32_16x16x32_bf16 v[104:107], v[164:167], v[228:231], v[104:107]
	v_mfma_f32_16x16x32_bf16 v[96:99], v[164:167], v[236:239], v[96:99]
	v_mfma_f32_16x16x32_bf16 v[100:103], v[128:131], v[236:239], v[100:103]
	v_mfma_f32_16x16x32_bf16 v[124:127], v[132:135], v[216:219], v[124:127]
	v_mfma_f32_16x16x32_bf16 v[120:123], v[168:171], v[216:219], v[120:123]
	v_mfma_f32_16x16x32_bf16 v[112:115], v[168:171], v[224:227], v[112:115]
	v_mfma_f32_16x16x32_bf16 v[116:119], v[132:135], v[224:227], v[116:119]
	v_mfma_f32_16x16x32_bf16 v[108:111], v[132:135], v[232:235], v[108:111]
	v_mfma_f32_16x16x32_bf16 v[104:107], v[168:171], v[232:235], v[104:107]
	v_mfma_f32_16x16x32_bf16 v[96:99], v[168:171], v[240:243], v[96:99]
	v_mfma_f32_16x16x32_bf16 v[100:103], v[132:135], v[240:243], v[100:103]
	s_setprio 0
	s_setprio 1
	v_mfma_f32_16x16x32_bf16 v[60:63], v[172:175], v[212:215], v[60:63]
	v_mfma_f32_16x16x32_bf16 v[56:59], v[184:187], v[212:215], v[56:59]
	v_mfma_f32_16x16x32_bf16 v[48:51], v[184:187], v[220:223], v[48:51]
	v_mfma_f32_16x16x32_bf16 v[52:55], v[172:175], v[220:223], v[52:55]
	v_mfma_f32_16x16x32_bf16 v[44:47], v[172:175], v[228:231], v[44:47]
	v_mfma_f32_16x16x32_bf16 v[40:43], v[184:187], v[228:231], v[40:43]
	v_mfma_f32_16x16x32_bf16 v[32:35], v[184:187], v[236:239], v[32:35]
	v_mfma_f32_16x16x32_bf16 v[36:39], v[172:175], v[236:239], v[36:39]
	v_mfma_f32_16x16x32_bf16 v[60:63], v[180:183], v[216:219], v[60:63]
	v_mfma_f32_16x16x32_bf16 v[56:59], v[208:211], v[216:219], v[56:59]
	v_mfma_f32_16x16x32_bf16 v[48:51], v[208:211], v[224:227], v[48:51]
	v_mfma_f32_16x16x32_bf16 v[52:55], v[180:183], v[224:227], v[52:55]
	v_mfma_f32_16x16x32_bf16 v[44:47], v[180:183], v[232:235], v[44:47]
	v_mfma_f32_16x16x32_bf16 v[40:43], v[208:211], v[232:235], v[40:43]
	v_mfma_f32_16x16x32_bf16 v[32:35], v[208:211], v[240:243], v[32:35]
	v_mfma_f32_16x16x32_bf16 v[36:39], v[180:183], v[240:243], v[36:39]
	s_setprio 0
	s_barrier
	s_add_i32 s34, s34, s35
	v_lshl_add_u64 v[188:189], s[58:59], 0, v[140:141]
	s_mov_b32 m0, s34
	ds_read_b128 v[212:215], v179 offset:16384
	ds_read_b128 v[216:219], v179 offset:17408
	ds_read_b128 v[220:223], v179 offset:18432
	ds_read_b128 v[224:227], v179 offset:19456
	ds_read_b128 v[228:231], v179 offset:20480
	ds_read_b128 v[232:235], v179 offset:21504
	ds_read_b128 v[236:239], v179 offset:22528
	ds_read_b128 v[240:243], v179 offset:23552
	global_load_lds_dwordx4 v[188:189], off
	s_add_i32 m0, s34, 0x2000
	s_add_u32 s54, s58, 0x2c000
	v_lshl_add_u64 v[244:245], s[58:59], 0, v[136:137]
	s_addc_u32 s55, s59, 0
	s_add_i32 s34, s37, s35
	global_load_lds_dwordx4 v[244:245], off
	v_lshl_add_u64 v[246:247], s[54:55], 0, v[140:141]
	s_mov_b32 m0, s34
	v_lshl_add_u64 v[248:249], s[60:61], 0, v[138:139]
	global_load_lds_dwordx4 v[246:247], off
	v_lshl_add_u64 v[246:247], s[54:55], 0, v[136:137]
	s_add_i32 m0, s34, 0x2000
	s_nop 0
	global_load_lds_dwordx4 v[246:247], off
	v_lshl_add_u64 v[246:247], s[60:61], 0, v[142:143]
	s_mov_b32 m0, s62
	s_nop 0
	global_load_lds_dwordx4 v[246:247], off
	s_mov_b32 m0, s63
	s_nop 0
	global_load_lds_dwordx4 v[248:249], off
	s_waitcnt vmcnt(8)
	s_waitcnt lgkmcnt(0)
	s_barrier
	s_setprio 1
	s_waitcnt lgkmcnt(0)
	v_mfma_f32_16x16x32_bf16 v[92:95], v[128:131], v[212:215], v[92:95]
	v_mfma_f32_16x16x32_bf16 v[88:91], v[164:167], v[212:215], v[88:91]
	v_mfma_f32_16x16x32_bf16 v[80:83], v[164:167], v[220:223], v[80:83]
	v_mfma_f32_16x16x32_bf16 v[84:87], v[128:131], v[220:223], v[84:87]
	v_mfma_f32_16x16x32_bf16 v[76:79], v[128:131], v[228:231], v[76:79]
	v_mfma_f32_16x16x32_bf16 v[72:75], v[164:167], v[228:231], v[72:75]
	v_mfma_f32_16x16x32_bf16 v[64:67], v[164:167], v[236:239], v[64:67]
	v_mfma_f32_16x16x32_bf16 v[68:71], v[128:131], v[236:239], v[68:71]
	v_mfma_f32_16x16x32_bf16 v[92:95], v[132:135], v[216:219], v[92:95]
	v_mfma_f32_16x16x32_bf16 v[88:91], v[168:171], v[216:219], v[88:91]
	v_mfma_f32_16x16x32_bf16 v[80:83], v[168:171], v[224:227], v[80:83]
	v_mfma_f32_16x16x32_bf16 v[84:87], v[132:135], v[224:227], v[84:87]
	v_mfma_f32_16x16x32_bf16 v[76:79], v[132:135], v[232:235], v[76:79]
	v_mfma_f32_16x16x32_bf16 v[72:75], v[168:171], v[232:235], v[72:75]
	v_mfma_f32_16x16x32_bf16 v[64:67], v[168:171], v[240:243], v[64:67]
	v_mfma_f32_16x16x32_bf16 v[68:71], v[132:135], v[240:243], v[68:71]
	s_setprio 0
	s_setprio 1
	v_mfma_f32_16x16x32_bf16 v[28:31], v[172:175], v[212:215], v[28:31]
	v_mfma_f32_16x16x32_bf16 v[24:27], v[184:187], v[212:215], v[24:27]
	v_mfma_f32_16x16x32_bf16 v[16:19], v[184:187], v[220:223], v[16:19]
	v_mfma_f32_16x16x32_bf16 v[20:23], v[172:175], v[220:223], v[20:23]
	v_mfma_f32_16x16x32_bf16 v[12:15], v[172:175], v[228:231], v[12:15]
	v_mfma_f32_16x16x32_bf16 v[8:11], v[184:187], v[228:231], v[8:11]
	v_mfma_f32_16x16x32_bf16 v[0:3], v[184:187], v[236:239], v[0:3]
	v_mfma_f32_16x16x32_bf16 v[4:7], v[172:175], v[236:239], v[4:7]
	v_mfma_f32_16x16x32_bf16 v[28:31], v[180:183], v[216:219], v[28:31]
	v_mfma_f32_16x16x32_bf16 v[24:27], v[208:211], v[216:219], v[24:27]
	v_mfma_f32_16x16x32_bf16 v[16:19], v[208:211], v[224:227], v[16:19]
	v_mfma_f32_16x16x32_bf16 v[20:23], v[180:183], v[224:227], v[20:23]
	v_mfma_f32_16x16x32_bf16 v[12:15], v[180:183], v[232:235], v[12:15]
	v_mfma_f32_16x16x32_bf16 v[8:11], v[208:211], v[232:235], v[8:11]
	v_mfma_f32_16x16x32_bf16 v[0:3], v[208:211], v[240:243], v[0:3]
	v_mfma_f32_16x16x32_bf16 v[4:7], v[180:183], v[240:243], v[4:7]
	s_setprio 0
	s_barrier
	s_add_i32 s34, 0, 0x18000
	s_add_i32 s37, 0, 0x1c000
	v_add_u32_e32 v168, s34, v178
	v_add_u32_e32 v207, s37, v178
	ds_read_b128 v[128:131], v168
	ds_read_b128 v[132:135], v168 offset:1024
	ds_read_b128 v[164:167], v168 offset:2048
	ds_read_b128 v[168:171], v168 offset:3072
	ds_read_b128 v[172:175], v207
	ds_read_b128 v[180:183], v207 offset:1024
	ds_read_b128 v[184:187], v207 offset:2048
	ds_read_b128 v[208:211], v207 offset:3072
	s_add_u32 s54, s60, 0xb0000
	s_addc_u32 s55, s61, 0
	s_mov_b32 m0, s64
	v_lshl_add_u64 v[250:251], s[54:55], 0, v[142:143]
	ds_read_b128 v[212:215], v179 offset:32768
	ds_read_b128 v[216:219], v179 offset:33792
	ds_read_b128 v[220:223], v179 offset:34816
	ds_read_b128 v[224:227], v179 offset:35840
	ds_read_b128 v[228:231], v179 offset:36864
	ds_read_b128 v[232:235], v179 offset:37888
	ds_read_b128 v[236:239], v179 offset:38912
	ds_read_b128 v[240:243], v179 offset:39936
	global_load_lds_dwordx4 v[250:251], off
	v_lshl_add_u64 v[250:251], s[54:55], 0, v[138:139]
	s_mov_b32 m0, s65
	s_nop 0
	global_load_lds_dwordx4 v[250:251], off
	s_waitcnt vmcnt(8)
	s_waitcnt lgkmcnt(0)
	s_barrier
	s_setprio 1
	s_waitcnt lgkmcnt(0)
	v_mfma_f32_16x16x32_bf16 v[124:127], v[128:131], v[212:215], v[124:127]
	v_mfma_f32_16x16x32_bf16 v[120:123], v[164:167], v[212:215], v[120:123]
	v_mfma_f32_16x16x32_bf16 v[112:115], v[164:167], v[220:223], v[112:115]
	v_mfma_f32_16x16x32_bf16 v[116:119], v[128:131], v[220:223], v[116:119]
	v_mfma_f32_16x16x32_bf16 v[108:111], v[128:131], v[228:231], v[108:111]
	v_mfma_f32_16x16x32_bf16 v[104:107], v[164:167], v[228:231], v[104:107]
	v_mfma_f32_16x16x32_bf16 v[96:99], v[164:167], v[236:239], v[96:99]
	v_mfma_f32_16x16x32_bf16 v[100:103], v[128:131], v[236:239], v[100:103]
	v_mfma_f32_16x16x32_bf16 v[124:127], v[132:135], v[216:219], v[124:127]
	v_mfma_f32_16x16x32_bf16 v[120:123], v[168:171], v[216:219], v[120:123]
	v_mfma_f32_16x16x32_bf16 v[112:115], v[168:171], v[224:227], v[112:115]
	v_mfma_f32_16x16x32_bf16 v[116:119], v[132:135], v[224:227], v[116:119]
	v_mfma_f32_16x16x32_bf16 v[108:111], v[132:135], v[232:235], v[108:111]
	v_mfma_f32_16x16x32_bf16 v[104:107], v[168:171], v[232:235], v[104:107]
	v_mfma_f32_16x16x32_bf16 v[96:99], v[168:171], v[240:243], v[96:99]
	v_mfma_f32_16x16x32_bf16 v[100:103], v[132:135], v[240:243], v[100:103]
	s_setprio 0
	s_setprio 1
	v_mfma_f32_16x16x32_bf16 v[60:63], v[172:175], v[212:215], v[60:63]
	v_mfma_f32_16x16x32_bf16 v[56:59], v[184:187], v[212:215], v[56:59]
	v_mfma_f32_16x16x32_bf16 v[48:51], v[184:187], v[220:223], v[48:51]
	v_mfma_f32_16x16x32_bf16 v[52:55], v[172:175], v[220:223], v[52:55]
	v_mfma_f32_16x16x32_bf16 v[44:47], v[172:175], v[228:231], v[44:47]
	v_mfma_f32_16x16x32_bf16 v[40:43], v[184:187], v[228:231], v[40:43]
	v_mfma_f32_16x16x32_bf16 v[32:35], v[184:187], v[236:239], v[32:35]
	v_mfma_f32_16x16x32_bf16 v[36:39], v[172:175], v[236:239], v[36:39]
	v_mfma_f32_16x16x32_bf16 v[60:63], v[180:183], v[216:219], v[60:63]
	v_mfma_f32_16x16x32_bf16 v[56:59], v[208:211], v[216:219], v[56:59]
	v_mfma_f32_16x16x32_bf16 v[48:51], v[208:211], v[224:227], v[48:51]
	v_mfma_f32_16x16x32_bf16 v[52:55], v[180:183], v[224:227], v[52:55]
	v_mfma_f32_16x16x32_bf16 v[44:47], v[180:183], v[232:235], v[44:47]
	v_mfma_f32_16x16x32_bf16 v[40:43], v[208:211], v[232:235], v[40:43]
	v_mfma_f32_16x16x32_bf16 v[32:35], v[208:211], v[240:243], v[32:35]
	v_mfma_f32_16x16x32_bf16 v[36:39], v[180:183], v[240:243], v[36:39]
	s_setprio 0
	s_barrier
	s_add_i32 s34, s34, s35
	v_lshl_add_u64 v[188:189], v[188:189], 0, s[26:27]
	s_mov_b32 m0, s34
	ds_read_b128 v[212:215], v179 offset:49152
	ds_read_b128 v[216:219], v179 offset:50176
	ds_read_b128 v[220:223], v179 offset:51200
	ds_read_b128 v[224:227], v179 offset:52224
	ds_read_b128 v[228:231], v179 offset:53248
	ds_read_b128 v[232:235], v179 offset:54272
	ds_read_b128 v[236:239], v179 offset:55296
	ds_read_b128 v[240:243], v179 offset:56320
	global_load_lds_dwordx4 v[188:189], off
	s_add_i32 m0, s34, 0x2000
	s_add_u32 s54, s58, 0x2c080
	v_lshl_add_u64 v[188:189], v[244:245], 0, s[26:27]
	s_addc_u32 s55, s59, 0
	s_add_i32 s34, s37, s35
	global_load_lds_dwordx4 v[188:189], off
	v_lshl_add_u64 v[188:189], s[54:55], 0, v[140:141]
	s_mov_b32 m0, s34
	s_nop 0
	global_load_lds_dwordx4 v[188:189], off
	v_lshl_add_u64 v[188:189], s[54:55], 0, v[136:137]
	s_add_i32 m0, s34, 0x2000
	s_nop 0
	global_load_lds_dwordx4 v[188:189], off
	v_lshl_add_u64 v[188:189], v[246:247], 0, s[26:27]
	s_mov_b32 m0, s66
	s_nop 0
	global_load_lds_dwordx4 v[188:189], off
	v_lshl_add_u64 v[188:189], v[248:249], 0, s[26:27]
	s_mov_b32 m0, s67
	s_nop 0
	global_load_lds_dwordx4 v[188:189], off
	s_waitcnt vmcnt(8)
	s_waitcnt lgkmcnt(0)
	s_barrier
	s_setprio 1
	s_waitcnt lgkmcnt(0)
	v_mfma_f32_16x16x32_bf16 v[92:95], v[128:131], v[212:215], v[92:95]
	v_mfma_f32_16x16x32_bf16 v[88:91], v[164:167], v[212:215], v[88:91]
	v_mfma_f32_16x16x32_bf16 v[80:83], v[164:167], v[220:223], v[80:83]
	v_mfma_f32_16x16x32_bf16 v[84:87], v[128:131], v[220:223], v[84:87]
	v_mfma_f32_16x16x32_bf16 v[76:79], v[128:131], v[228:231], v[76:79]
	v_mfma_f32_16x16x32_bf16 v[72:75], v[164:167], v[228:231], v[72:75]
	v_mfma_f32_16x16x32_bf16 v[64:67], v[164:167], v[236:239], v[64:67]
	v_mfma_f32_16x16x32_bf16 v[68:71], v[128:131], v[236:239], v[68:71]
	v_mfma_f32_16x16x32_bf16 v[92:95], v[132:135], v[216:219], v[92:95]
	v_mfma_f32_16x16x32_bf16 v[88:91], v[168:171], v[216:219], v[88:91]
	v_mfma_f32_16x16x32_bf16 v[80:83], v[168:171], v[224:227], v[80:83]
	v_mfma_f32_16x16x32_bf16 v[84:87], v[132:135], v[224:227], v[84:87]
	v_mfma_f32_16x16x32_bf16 v[76:79], v[132:135], v[232:235], v[76:79]
	v_mfma_f32_16x16x32_bf16 v[72:75], v[168:171], v[232:235], v[72:75]
	v_mfma_f32_16x16x32_bf16 v[64:67], v[168:171], v[240:243], v[64:67]
	v_mfma_f32_16x16x32_bf16 v[68:71], v[132:135], v[240:243], v[68:71]
	s_setprio 0
	s_setprio 1
	v_mfma_f32_16x16x32_bf16 v[28:31], v[172:175], v[212:215], v[28:31]
	v_mfma_f32_16x16x32_bf16 v[24:27], v[184:187], v[212:215], v[24:27]
	v_mfma_f32_16x16x32_bf16 v[16:19], v[184:187], v[220:223], v[16:19]
	v_mfma_f32_16x16x32_bf16 v[20:23], v[172:175], v[220:223], v[20:23]
	v_mfma_f32_16x16x32_bf16 v[12:15], v[172:175], v[228:231], v[12:15]
	v_mfma_f32_16x16x32_bf16 v[8:11], v[184:187], v[228:231], v[8:11]
	v_mfma_f32_16x16x32_bf16 v[0:3], v[184:187], v[236:239], v[0:3]
	v_mfma_f32_16x16x32_bf16 v[4:7], v[172:175], v[236:239], v[4:7]
	v_mfma_f32_16x16x32_bf16 v[28:31], v[180:183], v[216:219], v[28:31]
	v_mfma_f32_16x16x32_bf16 v[24:27], v[208:211], v[216:219], v[24:27]
	v_mfma_f32_16x16x32_bf16 v[16:19], v[208:211], v[224:227], v[16:19]
	v_mfma_f32_16x16x32_bf16 v[20:23], v[180:183], v[224:227], v[20:23]
	v_mfma_f32_16x16x32_bf16 v[12:15], v[180:183], v[232:235], v[12:15]
	v_mfma_f32_16x16x32_bf16 v[8:11], v[208:211], v[232:235], v[8:11]
	v_mfma_f32_16x16x32_bf16 v[0:3], v[208:211], v[240:243], v[0:3]
	v_mfma_f32_16x16x32_bf16 v[4:7], v[180:183], v[240:243], v[4:7]
	s_setprio 0
	s_barrier
	s_add_i32 s49, s49, 2
	s_add_u32 vcc_hi, vcc_hi, 0x100
	s_addc_u32 s48, s48, 0
	s_cmp_gt_u32 s49, 41
	s_mov_b64 s[54:55], s[56:57]
	s_cbranch_scc0 .LBB0_1251
	v_readlane_b32 s4, v252, 28
	v_readlane_b32 s5, v252, 29
	s_and_b64 vcc, exec, s[4:5]
	s_cbranch_vccz .LBB0_1254
	s_barrier
